# GEMM loops: LDS-write completion barrier moved behind the staged global-load issue so loads start before the block-wide sync
# speedup vs baseline: 1.0073x; 1.0073x over previous
; DEV f32x4 mfma16(bf16x8 a, bf16x8 b, f32x4 c) { return __builtin_amdgcn_mfma_f32_16x16x32_bf16(a, b, c, 0, 0, 0); }
; #define G_LOAD(RA, RB, KT) { _Pragma("unroll") for (int i = 0; i < 4; i++) { \
;       RA[i] = *(const u32x4*)(Ap + (size_t)(i * 32) * lda + (KT) * 64); RB[i] = *(const u32x4*)(Bp + (size_t)(i * 32) * ldb + (KT) * 64); } }
; #define G_STORE(RA, RB) { _Pragma("unroll") for (int i = 0; i < 4; i++) { \
;       *(u32x4*)(As + (lrow + i * 32) * GLD + lcc * 8) = RA[i]; *(u32x4*)(Bs + (lrow + i * 32) * GLD + lcc * 8) = RB[i]; } }
; template <int TI, int TJ, int KS>
; DEV void mfma_lds(const bf16_t* Arows, int lda, const bf16_t* Brows, int ldb, int i0, int j0, f32x4 (&acc)[TI][TJ]) {
;     ...
;   for (int ks = 0; ks < KS; ks++) {
;     bf16x8 af[TI], bfr[TJ];
; #pragma unroll
;     for (int i = 0; i < TI; i++) af[i] = *(const bf16x8*)(Arows + (i0 + i * 16 + l15) * lda + ks * 32 + quad * 8);
; #pragma unroll
;     for (int j = 0; j < TJ; j++) bfr[j] = *(const bf16x8*)(Brows + (j0 + j * 16 + l15) * ldb + ks * 32 + quad * 8);
; #pragma unroll
;     for (int i = 0; i < TI; i++)
; #pragma unroll
;       for (int j = 0; j < TJ; j++) acc[i][j] = mfma16(af[i], bfr[j], acc[i][j]);
;   }
; template <class Epi>
; DEV void gemm_tile(const bf16_t* __restrict__ A, int lda, const bf16_t* __restrict__ Bt, int ldb, int K, int m0, int n0,
;                    Epi& epi, char* smem) {
;     ...
;   for (int kt = 0; kt < nk; kt += 2) {
;     __syncthreads();
;     G_STORE(ra0, rb0);
;     __syncthreads();
;     if (kt + 2 < nk) G_LOAD(ra0, rb0, kt + 2);
;     mfma_lds<4, 4, 2>(Bs, GLD, As, GLD, wn * 64, wm * 64, acc);
;     __syncthreads();
;     G_STORE(ra1, rb1);
;     __syncthreads();
;     if (kt + 3 < nk) G_LOAD(ra1, rb1, kt + 3);
;     mfma_lds<4, 4, 2>(Bs, GLD, As, GLD, wn * 64, wm * 64, acc);
;   }
.LBB0_181:
	s_barrier
	v_mov_b32_e32 v130, v195
	v_and_b32_e32 v135, 15, v130
	v_or_b32_e32 v131, v135, v144
	v_and_b32_e32 v148, 48, v130
	v_mul_u32_u24_e32 v130, 0x50, v131
	v_lshl_add_u32 v147, v130, 1, v148
	v_or_b32_e32 v135, v135, v146
	v_mad_u32_u24 v238, v135, s36, v148
	v_lshl_add_u64 v[136:137], v[136:137], 0, s[34:35]
	v_lshl_add_u64 v[138:139], v[138:139], 0, s[34:35]
	s_andn2_b64 vcc, exec, s[14:15]
	ds_read_b128 v[148:151], v147 offset:20480
	ds_read_b128 v[164:167], v238
	ds_read_b128 v[168:171], v238 offset:2560
	ds_read_b128 v[172:175], v238 offset:5120
	ds_read_b128 v[176:179], v238 offset:7680
	ds_read_b128 v[152:155], v147 offset:23040
	ds_read_b128 v[156:159], v147 offset:25600
	ds_read_b128 v[160:163], v147 offset:28160
	ds_read_b128 v[180:183], v238 offset:64
	ds_read_b128 v[184:187], v238 offset:2624
	s_waitcnt lgkmcnt(8)
	v_mfma_f32_16x16x32_bf16 v[106:109], v[148:151], v[164:167], v[106:109]
	s_waitcnt lgkmcnt(7)
	v_mfma_f32_16x16x32_bf16 v[122:125], v[148:151], v[168:171], v[122:125]
	s_waitcnt lgkmcnt(6)
	v_mfma_f32_16x16x32_bf16 v[114:117], v[148:151], v[172:175], v[114:117]
	s_waitcnt lgkmcnt(5)
	v_mfma_f32_16x16x32_bf16 v[110:113], v[148:151], v[176:179], v[110:113]
	ds_read_b128 v[148:151], v147 offset:20544
	s_waitcnt lgkmcnt(5)
	v_mfma_f32_16x16x32_bf16 v[102:105], v[152:155], v[164:167], v[102:105]
	v_mfma_f32_16x16x32_bf16 v[94:97], v[152:155], v[168:171], v[94:97]
	v_mfma_f32_16x16x32_bf16 v[86:89], v[152:155], v[172:175], v[86:89]
	v_mfma_f32_16x16x32_bf16 v[78:81], v[152:155], v[176:179], v[78:81]
	ds_read_b128 v[152:155], v147 offset:23104
	s_waitcnt lgkmcnt(5)
	v_mfma_f32_16x16x32_bf16 v[82:85], v[156:159], v[164:167], v[82:85]
	v_mfma_f32_16x16x32_bf16 v[74:77], v[156:159], v[168:171], v[74:77]
	v_mfma_f32_16x16x32_bf16 v[70:73], v[156:159], v[172:175], v[70:73]
	v_mfma_f32_16x16x32_bf16 v[66:69], v[156:159], v[176:179], v[66:69]
	ds_read_b128 v[156:159], v147 offset:25664
	s_waitcnt lgkmcnt(5)
	v_mfma_f32_16x16x32_bf16 v[126:129], v[160:163], v[172:175], v[126:129]
	v_mfma_f32_16x16x32_bf16 v[118:121], v[160:163], v[176:179], v[118:121]
	ds_read_b128 v[172:175], v238 offset:5184
	ds_read_b128 v[176:179], v238 offset:7744
	v_mfma_f32_16x16x32_bf16 v[98:101], v[160:163], v[164:167], v[98:101]
	v_mfma_f32_16x16x32_bf16 v[90:93], v[160:163], v[168:171], v[90:93]
	ds_read_b128 v[160:163], v147 offset:28224
	s_waitcnt lgkmcnt(5)
	v_mfma_f32_16x16x32_bf16 v[106:109], v[148:151], v[180:183], v[106:109]
	s_waitcnt lgkmcnt(4)
	v_mfma_f32_16x16x32_bf16 v[102:105], v[152:155], v[180:183], v[102:105]
	s_waitcnt lgkmcnt(3)
	v_mfma_f32_16x16x32_bf16 v[82:85], v[156:159], v[180:183], v[82:85]
	v_mfma_f32_16x16x32_bf16 v[122:125], v[148:151], v[184:187], v[122:125]
	v_mfma_f32_16x16x32_bf16 v[94:97], v[152:155], v[184:187], v[94:97]
	v_mfma_f32_16x16x32_bf16 v[74:77], v[156:159], v[184:187], v[74:77]
	s_waitcnt lgkmcnt(2)
	v_mfma_f32_16x16x32_bf16 v[114:117], v[148:151], v[172:175], v[114:117]
	v_mfma_f32_16x16x32_bf16 v[86:89], v[152:155], v[172:175], v[86:89]
	v_mfma_f32_16x16x32_bf16 v[70:73], v[156:159], v[172:175], v[70:73]
	s_waitcnt lgkmcnt(1)
	v_mfma_f32_16x16x32_bf16 v[110:113], v[148:151], v[176:179], v[110:113]
	v_mfma_f32_16x16x32_bf16 v[78:81], v[152:155], v[176:179], v[78:81]
	v_mfma_f32_16x16x32_bf16 v[66:69], v[156:159], v[176:179], v[66:69]
	s_waitcnt lgkmcnt(0)
	v_mfma_f32_16x16x32_bf16 v[98:101], v[160:163], v[180:183], v[98:101]
	v_mfma_f32_16x16x32_bf16 v[90:93], v[160:163], v[184:187], v[90:93]
	v_mfma_f32_16x16x32_bf16 v[126:129], v[160:163], v[172:175], v[126:129]
	v_mfma_f32_16x16x32_bf16 v[118:121], v[160:163], v[176:179], v[118:121]
	s_cbranch_vccz .LBB0_177
.LBB0_182:
	s_add_i32 s12, s12, 2
	s_cmp_gt_u32 s12, 13
	s_cselect_b64 s[14:15], -1, 0
	s_and_b64 vcc, exec, s[14:15]
	v_lshl_add_u64 v[142:143], v[138:139], 0, v[0:1]
	v_lshl_add_u64 v[140:141], v[136:137], 0, v[0:1]
	s_waitcnt lgkmcnt(0)
	s_barrier
	s_waitcnt vmcnt(8)
	ds_write_b128 v134, v[2:5]
	ds_write_b128 v134, v[10:13] offset:20480
	ds_write_b128 v134, v[18:21] offset:5120
	ds_write_b128 v134, v[26:29] offset:25600
	ds_write_b128 v134, v[34:37] offset:10240
	ds_write_b128 v134, v[42:45] offset:30720
	ds_write_b128 v134, v[50:53] offset:15360
	ds_write_b128 v134, v[58:61] offset:35840
	s_waitcnt lgkmcnt(0)
	s_cbranch_vccnz .Lgw_skip_0
	v_add_co_u32_e32 v2, vcc, 0x4200000, v142
	s_nop 1
	v_addc_co_u32_e32 v3, vcc, 0, v143, vcc
	v_add_co_u32_e32 v10, vcc, 0xba00000, v140
	global_load_dwordx4 v[2:5], v[2:3], off offset:256
	s_nop 0
	v_addc_co_u32_e32 v11, vcc, 0, v141, vcc
	v_add_co_u32_e32 v18, vcc, 0x4211000, v142
	global_load_dwordx4 v[10:13], v[10:11], off offset:256
	s_nop 0
	v_addc_co_u32_e32 v19, vcc, 0, v143, vcc
	v_add_co_u32_e32 v26, vcc, 0xba11000, v140
	global_load_dwordx4 v[18:21], v[18:19], off offset:256
	s_nop 0
	v_addc_co_u32_e32 v27, vcc, 0, v141, vcc
	v_add_co_u32_e32 v34, vcc, 0x4222000, v142
	global_load_dwordx4 v[26:29], v[26:27], off offset:256
	s_nop 0
	v_addc_co_u32_e32 v35, vcc, 0, v143, vcc
	v_add_co_u32_e32 v42, vcc, 0xba22000, v140
	global_load_dwordx4 v[34:37], v[34:35], off offset:256
	s_nop 0
	v_addc_co_u32_e32 v43, vcc, 0, v141, vcc
	v_add_co_u32_e32 v50, vcc, 0x4233000, v142
	global_load_dwordx4 v[42:45], v[42:43], off offset:256
	s_nop 0
	v_addc_co_u32_e32 v51, vcc, 0, v143, vcc
	v_add_co_u32_e32 v58, vcc, 0xba33000, v140
	global_load_dwordx4 v[50:53], v[50:51], off offset:256
	s_nop 0
	v_addc_co_u32_e32 v59, vcc, 0, v141, vcc
	global_load_dwordx4 v[58:61], v[58:59], off offset:256
; DEV f32x4 mfma16(bf16x8 a, bf16x8 b, f32x4 c) { return __builtin_amdgcn_mfma_f32_16x16x32_bf16(a, b, c, 0, 0, 0); }
; #define G_LOAD(RA, RB, KT) { _Pragma("unroll") for (int i = 0; i < 4; i++) { \
;       RA[i] = *(const u32x4*)(Ap + (size_t)(i * 32) * lda + (KT) * 64); RB[i] = *(const u32x4*)(Bp + (size_t)(i * 32) * ldb + (KT) * 64); } }
; #define G_STORE(RA, RB) { _Pragma("unroll") for (int i = 0; i < 4; i++) { \
;       *(u32x4*)(As + (lrow + i * 32) * GLD + lcc * 8) = RA[i]; *(u32x4*)(Bs + (lrow + i * 32) * GLD + lcc * 8) = RB[i]; } }
; template <int TI, int TJ, int KS>
; DEV void mfma_lds(const bf16_t* Arows, int lda, const bf16_t* Brows, int ldb, int i0, int j0, f32x4 (&acc)[TI][TJ]) {
;     ...
;   for (int ks = 0; ks < KS; ks++) {
;     bf16x8 af[TI], bfr[TJ];
; #pragma unroll
;     for (int i = 0; i < TI; i++) af[i] = *(const bf16x8*)(Arows + (i0 + i * 16 + l15) * lda + ks * 32 + quad * 8);
; #pragma unroll
;     for (int j = 0; j < TJ; j++) bfr[j] = *(const bf16x8*)(Brows + (j0 + j * 16 + l15) * ldb + ks * 32 + quad * 8);
; #pragma unroll
;     for (int i = 0; i < TI; i++)
; #pragma unroll
;       for (int j = 0; j < TJ; j++) acc[i][j] = mfma16(af[i], bfr[j], acc[i][j]);
;   }
; template <class Epi>
; DEV void gemm_tile(const bf16_t* __restrict__ A, int lda, const bf16_t* __restrict__ Bt, int ldb, int K, int m0, int n0,
;                    Epi& epi, char* smem) {
;     ...
;   for (int kt = 0; kt < nk; kt += 2) {
;     __syncthreads();
;     G_STORE(ra0, rb0);
;     __syncthreads();
;     if (kt + 2 < nk) G_LOAD(ra0, rb0, kt + 2);
;     mfma_lds<4, 4, 2>(Bs, GLD, As, GLD, wn * 64, wm * 64, acc);
;     __syncthreads();
;     G_STORE(ra1, rb1);
;     __syncthreads();
;     if (kt + 3 < nk) G_LOAD(ra1, rb1, kt + 3);
;     mfma_lds<4, 4, 2>(Bs, GLD, As, GLD, wn * 64, wm * 64, acc);
;   }
.LBB0_184:
	s_barrier
	v_mov_b32_e32 v130, v195
	s_cmp_gt_u32 s12, 12
	v_and_b32_e32 v135, 15, v130
	v_or_b32_e32 v131, v135, v144
	v_and_b32_e32 v148, 48, v130
	v_mul_u32_u24_e32 v130, 0x50, v131
	v_lshl_add_u32 v147, v130, 1, v148
	v_or_b32_e32 v135, v135, v146
	v_mad_u32_u24 v238, v135, s36, v148
	ds_read_b128 v[148:151], v147 offset:20480
	ds_read_b128 v[164:167], v238
	ds_read_b128 v[168:171], v238 offset:2560
	ds_read_b128 v[172:175], v238 offset:5120
	ds_read_b128 v[176:179], v238 offset:7680
	ds_read_b128 v[152:155], v147 offset:23040
	ds_read_b128 v[156:159], v147 offset:25600
	ds_read_b128 v[160:163], v147 offset:28160
	ds_read_b128 v[180:183], v238 offset:64
	ds_read_b128 v[184:187], v238 offset:2624
	s_waitcnt lgkmcnt(8)
	v_mfma_f32_16x16x32_bf16 v[106:109], v[148:151], v[164:167], v[106:109]
	s_waitcnt lgkmcnt(7)
	v_mfma_f32_16x16x32_bf16 v[122:125], v[148:151], v[168:171], v[122:125]
	s_waitcnt lgkmcnt(6)
	v_mfma_f32_16x16x32_bf16 v[114:117], v[148:151], v[172:175], v[114:117]
	s_waitcnt lgkmcnt(5)
	v_mfma_f32_16x16x32_bf16 v[110:113], v[148:151], v[176:179], v[110:113]
	ds_read_b128 v[148:151], v147 offset:20544
	s_waitcnt lgkmcnt(5)
	v_mfma_f32_16x16x32_bf16 v[102:105], v[152:155], v[164:167], v[102:105]
	v_mfma_f32_16x16x32_bf16 v[94:97], v[152:155], v[168:171], v[94:97]
	v_mfma_f32_16x16x32_bf16 v[86:89], v[152:155], v[172:175], v[86:89]
	v_mfma_f32_16x16x32_bf16 v[78:81], v[152:155], v[176:179], v[78:81]
	ds_read_b128 v[152:155], v147 offset:23104
	s_waitcnt lgkmcnt(5)
	v_mfma_f32_16x16x32_bf16 v[82:85], v[156:159], v[164:167], v[82:85]
	v_mfma_f32_16x16x32_bf16 v[74:77], v[156:159], v[168:171], v[74:77]
	v_mfma_f32_16x16x32_bf16 v[70:73], v[156:159], v[172:175], v[70:73]
	v_mfma_f32_16x16x32_bf16 v[66:69], v[156:159], v[176:179], v[66:69]
	ds_read_b128 v[156:159], v147 offset:25664
	s_waitcnt lgkmcnt(5)
	v_mfma_f32_16x16x32_bf16 v[126:129], v[160:163], v[172:175], v[126:129]
	v_mfma_f32_16x16x32_bf16 v[118:121], v[160:163], v[176:179], v[118:121]
	ds_read_b128 v[172:175], v238 offset:5184
	ds_read_b128 v[176:179], v238 offset:7744
	v_mfma_f32_16x16x32_bf16 v[98:101], v[160:163], v[164:167], v[98:101]
	v_mfma_f32_16x16x32_bf16 v[90:93], v[160:163], v[168:171], v[90:93]
	ds_read_b128 v[160:163], v147 offset:28224
	s_waitcnt lgkmcnt(5)
	v_mfma_f32_16x16x32_bf16 v[106:109], v[148:151], v[180:183], v[106:109]
	s_waitcnt lgkmcnt(4)
	v_mfma_f32_16x16x32_bf16 v[102:105], v[152:155], v[180:183], v[102:105]
	s_waitcnt lgkmcnt(3)
	v_mfma_f32_16x16x32_bf16 v[82:85], v[156:159], v[180:183], v[82:85]
	v_mfma_f32_16x16x32_bf16 v[122:125], v[148:151], v[184:187], v[122:125]
	v_mfma_f32_16x16x32_bf16 v[94:97], v[152:155], v[184:187], v[94:97]
	v_mfma_f32_16x16x32_bf16 v[74:77], v[156:159], v[184:187], v[74:77]
	s_waitcnt lgkmcnt(2)
	v_mfma_f32_16x16x32_bf16 v[114:117], v[148:151], v[172:175], v[114:117]
	v_mfma_f32_16x16x32_bf16 v[86:89], v[152:155], v[172:175], v[86:89]
	v_mfma_f32_16x16x32_bf16 v[70:73], v[156:159], v[172:175], v[70:73]
	s_waitcnt lgkmcnt(1)
	v_mfma_f32_16x16x32_bf16 v[110:113], v[148:151], v[176:179], v[110:113]
	v_mfma_f32_16x16x32_bf16 v[78:81], v[152:155], v[176:179], v[78:81]
	v_mfma_f32_16x16x32_bf16 v[66:69], v[156:159], v[176:179], v[66:69]
	s_waitcnt lgkmcnt(0)
	v_mfma_f32_16x16x32_bf16 v[98:101], v[160:163], v[180:183], v[98:101]
	s_barrier
	v_mfma_f32_16x16x32_bf16 v[90:93], v[160:163], v[184:187], v[90:93]
	s_waitcnt vmcnt(8)
	ds_write_b128 v134, v[6:9]
	ds_write_b128 v134, v[14:17] offset:20480
	ds_write_b128 v134, v[22:25] offset:5120
	ds_write_b128 v134, v[30:33] offset:25600
	ds_write_b128 v134, v[38:41] offset:10240
	ds_write_b128 v134, v[46:49] offset:30720
	ds_write_b128 v134, v[54:57] offset:15360
	ds_write_b128 v134, v[62:65] offset:35840
	v_mfma_f32_16x16x32_bf16 v[126:129], v[160:163], v[172:175], v[126:129]
	s_waitcnt lgkmcnt(0)
	v_mfma_f32_16x16x32_bf16 v[118:121], v[160:163], v[176:179], v[118:121]
	s_cbranch_scc1 .LBB0_181
	v_add_co_u32_e32 v6, vcc, 0x4200000, v142
	s_nop 1
	v_addc_co_u32_e32 v7, vcc, 0, v143, vcc
	v_add_co_u32_e32 v14, vcc, 0xba00000, v140
	global_load_dwordx4 v[6:9], v[6:7], off offset:384
	s_nop 0
	v_addc_co_u32_e32 v15, vcc, 0, v141, vcc
	v_add_co_u32_e32 v22, vcc, 0x4211000, v142
	global_load_dwordx4 v[14:17], v[14:15], off offset:384
	s_nop 0
	v_addc_co_u32_e32 v23, vcc, 0, v143, vcc
	v_add_co_u32_e32 v30, vcc, 0xba11000, v140
	global_load_dwordx4 v[22:25], v[22:23], off offset:384
	s_nop 0
	v_addc_co_u32_e32 v31, vcc, 0, v141, vcc
	v_add_co_u32_e32 v38, vcc, 0x4222000, v142
	global_load_dwordx4 v[30:33], v[30:31], off offset:384
	s_nop 0
	v_addc_co_u32_e32 v39, vcc, 0, v143, vcc
	v_add_co_u32_e32 v46, vcc, 0xba22000, v140
	global_load_dwordx4 v[38:41], v[38:39], off offset:384
	s_nop 0
	v_addc_co_u32_e32 v47, vcc, 0, v141, vcc
	v_add_co_u32_e32 v54, vcc, 0x4233000, v142
	global_load_dwordx4 v[46:49], v[46:47], off offset:384
	s_nop 0
	v_addc_co_u32_e32 v55, vcc, 0, v143, vcc
	v_add_co_u32_e32 v62, vcc, 0xba33000, v140
	global_load_dwordx4 v[54:57], v[54:55], off offset:384
	s_nop 0
	v_addc_co_u32_e32 v63, vcc, 0, v141, vcc
	global_load_dwordx4 v[62:65], v[62:63], off offset:384
	s_branch .LBB0_181

; DEV f32x4 mfma16(bf16x8 a, bf16x8 b, f32x4 c) { return __builtin_amdgcn_mfma_f32_16x16x32_bf16(a, b, c, 0, 0, 0); }
; #define G_LOAD(RA, RB, KT) { _Pragma("unroll") for (int i = 0; i < 4; i++) { \
;       RA[i] = *(const u32x4*)(Ap + (size_t)(i * 32) * lda + (KT) * 64); RB[i] = *(const u32x4*)(Bp + (size_t)(i * 32) * ldb + (KT) * 64); } }
; #define G_STORE(RA, RB) { _Pragma("unroll") for (int i = 0; i < 4; i++) { \
;       *(u32x4*)(As + (lrow + i * 32) * GLD + lcc * 8) = RA[i]; *(u32x4*)(Bs + (lrow + i * 32) * GLD + lcc * 8) = RB[i]; } }
; template <int TI, int TJ, int KS>
; DEV void mfma_lds(const bf16_t* Arows, int lda, const bf16_t* Brows, int ldb, int i0, int j0, f32x4 (&acc)[TI][TJ]) {
;     ...
;   for (int ks = 0; ks < KS; ks++) {
;     bf16x8 af[TI], bfr[TJ];
; #pragma unroll
;     for (int i = 0; i < TI; i++) af[i] = *(const bf16x8*)(Arows + (i0 + i * 16 + l15) * lda + ks * 32 + quad * 8);
; #pragma unroll
;     for (int j = 0; j < TJ; j++) bfr[j] = *(const bf16x8*)(Brows + (j0 + j * 16 + l15) * ldb + ks * 32 + quad * 8);
; #pragma unroll
;     for (int i = 0; i < TI; i++)
; #pragma unroll
;       for (int j = 0; j < TJ; j++) acc[i][j] = mfma16(af[i], bfr[j], acc[i][j]);
;   }
; template <class Epi>
; DEV void gemm_tile(const bf16_t* __restrict__ A, int lda, const bf16_t* __restrict__ Bt, int ldb, int K, int m0, int n0,
;                    Epi& epi, char* smem) {
;     ...
;   for (int kt = 0; kt < nk; kt += 2) {
;     __syncthreads();
;     G_STORE(ra0, rb0);
;     __syncthreads();
;     if (kt + 2 < nk) G_LOAD(ra0, rb0, kt + 2);
;     mfma_lds<4, 4, 2>(Bs, GLD, As, GLD, wn * 64, wm * 64, acc);
;     __syncthreads();
;     G_STORE(ra1, rb1);
;     __syncthreads();
;     if (kt + 3 < nk) G_LOAD(ra1, rb1, kt + 3);
;     mfma_lds<4, 4, 2>(Bs, GLD, As, GLD, wn * 64, wm * 64, acc);
;   }
.LBB0_200:
	s_barrier
	v_mov_b32_e32 v131, v195
	v_and_b32_e32 v143, 15, v131
	v_or_b32_e32 v144, v143, v140
	v_and_b32_e32 v148, 48, v131
	v_mul_u32_u24_e32 v131, 0x50, v144
	v_lshl_add_u32 v131, v131, 1, v148
	v_or_b32_e32 v143, v143, v142
	v_mad_u32_u24 v238, v143, s36, v148
	v_lshl_add_u64 v[132:133], v[132:133], 0, s[34:35]
	v_lshl_add_u64 v[134:135], v[134:135], 0, s[34:35]
	s_and_b64 vcc, exec, s[16:17]
	ds_read_b128 v[144:147], v131 offset:20480
	ds_read_b128 v[160:163], v238
	ds_read_b128 v[164:167], v238 offset:2560
	ds_read_b128 v[168:171], v238 offset:5120
	ds_read_b128 v[172:175], v238 offset:7680
	ds_read_b128 v[148:151], v131 offset:23040
	ds_read_b128 v[152:155], v131 offset:25600
	ds_read_b128 v[156:159], v131 offset:28160
	ds_read_b128 v[176:179], v238 offset:64
	ds_read_b128 v[180:183], v238 offset:2624
	s_waitcnt lgkmcnt(8)
	v_mfma_f32_16x16x32_bf16 v[126:129], v[144:147], v[160:163], v[126:129]
	s_waitcnt lgkmcnt(7)
	v_mfma_f32_16x16x32_bf16 v[122:125], v[144:147], v[164:167], v[122:125]
	s_waitcnt lgkmcnt(6)
	v_mfma_f32_16x16x32_bf16 v[118:121], v[144:147], v[168:171], v[118:121]
	s_waitcnt lgkmcnt(5)
	v_mfma_f32_16x16x32_bf16 v[114:117], v[144:147], v[172:175], v[114:117]
	ds_read_b128 v[144:147], v131 offset:20544
	s_waitcnt lgkmcnt(5)
	v_mfma_f32_16x16x32_bf16 v[110:113], v[148:151], v[160:163], v[110:113]
	v_mfma_f32_16x16x32_bf16 v[74:77], v[148:151], v[164:167], v[74:77]
	v_mfma_f32_16x16x32_bf16 v[38:41], v[148:151], v[168:171], v[38:41]
	v_mfma_f32_16x16x32_bf16 v[34:37], v[148:151], v[172:175], v[34:37]
	ds_read_b128 v[148:151], v131 offset:23104
	s_waitcnt lgkmcnt(5)
	v_mfma_f32_16x16x32_bf16 v[30:33], v[152:155], v[160:163], v[30:33]
	v_mfma_f32_16x16x32_bf16 v[26:29], v[152:155], v[164:167], v[26:29]
	v_mfma_f32_16x16x32_bf16 v[22:25], v[152:155], v[168:171], v[22:25]
	v_mfma_f32_16x16x32_bf16 v[18:21], v[152:155], v[172:175], v[18:21]
	ds_read_b128 v[152:155], v131 offset:25664
	s_waitcnt lgkmcnt(5)
	v_mfma_f32_16x16x32_bf16 v[6:9], v[156:159], v[168:171], v[6:9]
	v_mfma_f32_16x16x32_bf16 v[2:5], v[156:159], v[172:175], v[2:5]
	ds_read_b128 v[168:171], v238 offset:5184
	ds_read_b128 v[172:175], v238 offset:7744
	v_mfma_f32_16x16x32_bf16 v[14:17], v[156:159], v[160:163], v[14:17]
	v_mfma_f32_16x16x32_bf16 v[10:13], v[156:159], v[164:167], v[10:13]
	ds_read_b128 v[156:159], v131 offset:28224
	s_waitcnt lgkmcnt(5)
	v_mfma_f32_16x16x32_bf16 v[126:129], v[144:147], v[176:179], v[126:129]
	s_waitcnt lgkmcnt(4)
	v_mfma_f32_16x16x32_bf16 v[110:113], v[148:151], v[176:179], v[110:113]
	s_waitcnt lgkmcnt(3)
	v_mfma_f32_16x16x32_bf16 v[30:33], v[152:155], v[176:179], v[30:33]
	v_mfma_f32_16x16x32_bf16 v[122:125], v[144:147], v[180:183], v[122:125]
	v_mfma_f32_16x16x32_bf16 v[74:77], v[148:151], v[180:183], v[74:77]
	v_mfma_f32_16x16x32_bf16 v[26:29], v[152:155], v[180:183], v[26:29]
	s_waitcnt lgkmcnt(2)
	v_mfma_f32_16x16x32_bf16 v[118:121], v[144:147], v[168:171], v[118:121]
	v_mfma_f32_16x16x32_bf16 v[38:41], v[148:151], v[168:171], v[38:41]
	v_mfma_f32_16x16x32_bf16 v[22:25], v[152:155], v[168:171], v[22:25]
	s_waitcnt lgkmcnt(1)
	v_mfma_f32_16x16x32_bf16 v[114:117], v[144:147], v[172:175], v[114:117]
	v_mfma_f32_16x16x32_bf16 v[34:37], v[148:151], v[172:175], v[34:37]
	v_mfma_f32_16x16x32_bf16 v[18:21], v[152:155], v[172:175], v[18:21]
	s_waitcnt lgkmcnt(0)
	v_mfma_f32_16x16x32_bf16 v[14:17], v[156:159], v[176:179], v[14:17]
	v_mfma_f32_16x16x32_bf16 v[10:13], v[156:159], v[180:183], v[10:13]
	v_mfma_f32_16x16x32_bf16 v[6:9], v[156:159], v[168:171], v[6:9]
	v_mfma_f32_16x16x32_bf16 v[2:5], v[156:159], v[172:175], v[2:5]
	s_cbranch_vccnz .LBB0_205
.LBB0_201:
	s_add_i32 s1, s1, 2
	s_cmp_gt_u32 s1, 13
	s_cselect_b64 s[16:17], -1, 0
	s_and_b64 vcc, exec, s[16:17]
	v_lshl_add_u64 v[138:139], v[134:135], 0, v[0:1]
	v_lshl_add_u64 v[136:137], v[132:133], 0, v[0:1]
	s_waitcnt lgkmcnt(0)
	s_barrier
	s_waitcnt vmcnt(8)
	ds_write_b128 v130, v[42:45]
	ds_write_b128 v130, v[50:53] offset:20480
	ds_write_b128 v130, v[58:61] offset:5120
	ds_write_b128 v130, v[66:69] offset:25600
	ds_write_b128 v130, v[78:81] offset:10240
	ds_write_b128 v130, v[86:89] offset:30720
	ds_write_b128 v130, v[94:97] offset:15360
	ds_write_b128 v130, v[102:105] offset:35840
	s_waitcnt lgkmcnt(0)
	s_cbranch_vccnz .Lgw_skip_1
	v_add_co_u32_e32 v42, vcc, 0x4200000, v138
	s_nop 1
	v_addc_co_u32_e32 v43, vcc, 0, v139, vcc
	v_add_co_u32_e32 v50, vcc, 0xb3a0000, v136
	global_load_dwordx4 v[42:45], v[42:43], off offset:256
	s_nop 0
	v_addc_co_u32_e32 v51, vcc, 0, v137, vcc
	v_add_co_u32_e32 v58, vcc, 0x4211000, v138
	global_load_dwordx4 v[50:53], v[50:51], off offset:256
	s_nop 0
	v_addc_co_u32_e32 v59, vcc, 0, v139, vcc
	v_add_co_u32_e32 v66, vcc, 0xb3b1000, v136
	global_load_dwordx4 v[58:61], v[58:59], off offset:256
	s_nop 0
	v_addc_co_u32_e32 v67, vcc, 0, v137, vcc
	v_add_co_u32_e32 v78, vcc, 0x4222000, v138
	global_load_dwordx4 v[66:69], v[66:67], off offset:256
	s_nop 0
	v_addc_co_u32_e32 v79, vcc, 0, v139, vcc
	v_add_co_u32_e32 v86, vcc, 0xb3c2000, v136
	global_load_dwordx4 v[78:81], v[78:79], off offset:256
	s_nop 0
	v_addc_co_u32_e32 v87, vcc, 0, v137, vcc
	v_add_co_u32_e32 v94, vcc, 0x4233000, v138
	global_load_dwordx4 v[86:89], v[86:87], off offset:256
	s_nop 0
	v_addc_co_u32_e32 v95, vcc, 0, v139, vcc
	v_add_co_u32_e32 v102, vcc, 0xb3d3000, v136
	global_load_dwordx4 v[94:97], v[94:95], off offset:256
	s_nop 0
	v_addc_co_u32_e32 v103, vcc, 0, v137, vcc
	global_load_dwordx4 v[102:105], v[102:103], off offset:256
; DEV f32x4 mfma16(bf16x8 a, bf16x8 b, f32x4 c) { return __builtin_amdgcn_mfma_f32_16x16x32_bf16(a, b, c, 0, 0, 0); }
; #define G_LOAD(RA, RB, KT) { _Pragma("unroll") for (int i = 0; i < 4; i++) { \
;       RA[i] = *(const u32x4*)(Ap + (size_t)(i * 32) * lda + (KT) * 64); RB[i] = *(const u32x4*)(Bp + (size_t)(i * 32) * ldb + (KT) * 64); } }
; #define G_STORE(RA, RB) { _Pragma("unroll") for (int i = 0; i < 4; i++) { \
;       *(u32x4*)(As + (lrow + i * 32) * GLD + lcc * 8) = RA[i]; *(u32x4*)(Bs + (lrow + i * 32) * GLD + lcc * 8) = RB[i]; } }
; template <int TI, int TJ, int KS>
; DEV void mfma_lds(const bf16_t* Arows, int lda, const bf16_t* Brows, int ldb, int i0, int j0, f32x4 (&acc)[TI][TJ]) {
;     ...
;   for (int ks = 0; ks < KS; ks++) {
;     bf16x8 af[TI], bfr[TJ];
; #pragma unroll
;     for (int i = 0; i < TI; i++) af[i] = *(const bf16x8*)(Arows + (i0 + i * 16 + l15) * lda + ks * 32 + quad * 8);
; #pragma unroll
;     for (int j = 0; j < TJ; j++) bfr[j] = *(const bf16x8*)(Brows + (j0 + j * 16 + l15) * ldb + ks * 32 + quad * 8);
; #pragma unroll
;     for (int i = 0; i < TI; i++)
; #pragma unroll
;       for (int j = 0; j < TJ; j++) acc[i][j] = mfma16(af[i], bfr[j], acc[i][j]);
;   }
; template <class Epi>
; DEV void gemm_tile(const bf16_t* __restrict__ A, int lda, const bf16_t* __restrict__ Bt, int ldb, int K, int m0, int n0,
;                    Epi& epi, char* smem) {
;     ...
;   for (int kt = 0; kt < nk; kt += 2) {
;     __syncthreads();
;     G_STORE(ra0, rb0);
;     __syncthreads();
;     if (kt + 2 < nk) G_LOAD(ra0, rb0, kt + 2);
;     mfma_lds<4, 4, 2>(Bs, GLD, As, GLD, wn * 64, wm * 64, acc);
;     __syncthreads();
;     G_STORE(ra1, rb1);
;     __syncthreads();
;     if (kt + 3 < nk) G_LOAD(ra1, rb1, kt + 3);
;     mfma_lds<4, 4, 2>(Bs, GLD, As, GLD, wn * 64, wm * 64, acc);
;   }
.LBB0_203:
	s_barrier
	v_mov_b32_e32 v131, v195
	s_cmp_gt_u32 s1, 12
	v_and_b32_e32 v143, 15, v131
	v_or_b32_e32 v144, v143, v140
	v_and_b32_e32 v148, 48, v131
	v_mul_u32_u24_e32 v131, 0x50, v144
	v_lshl_add_u32 v131, v131, 1, v148
	v_or_b32_e32 v143, v143, v142
	v_mad_u32_u24 v238, v143, s36, v148
	ds_read_b128 v[144:147], v131 offset:20480
	ds_read_b128 v[160:163], v238
	ds_read_b128 v[164:167], v238 offset:2560
	ds_read_b128 v[168:171], v238 offset:5120
	ds_read_b128 v[172:175], v238 offset:7680
	ds_read_b128 v[148:151], v131 offset:23040
	ds_read_b128 v[152:155], v131 offset:25600
	ds_read_b128 v[156:159], v131 offset:28160
	ds_read_b128 v[176:179], v238 offset:64
	ds_read_b128 v[180:183], v238 offset:2624
	s_waitcnt lgkmcnt(8)
	v_mfma_f32_16x16x32_bf16 v[126:129], v[144:147], v[160:163], v[126:129]
	s_waitcnt lgkmcnt(7)
	v_mfma_f32_16x16x32_bf16 v[122:125], v[144:147], v[164:167], v[122:125]
	s_waitcnt lgkmcnt(6)
	v_mfma_f32_16x16x32_bf16 v[118:121], v[144:147], v[168:171], v[118:121]
	s_waitcnt lgkmcnt(5)
	v_mfma_f32_16x16x32_bf16 v[114:117], v[144:147], v[172:175], v[114:117]
	ds_read_b128 v[144:147], v131 offset:20544
	s_waitcnt lgkmcnt(5)
	v_mfma_f32_16x16x32_bf16 v[110:113], v[148:151], v[160:163], v[110:113]
	v_mfma_f32_16x16x32_bf16 v[74:77], v[148:151], v[164:167], v[74:77]
	v_mfma_f32_16x16x32_bf16 v[38:41], v[148:151], v[168:171], v[38:41]
	v_mfma_f32_16x16x32_bf16 v[34:37], v[148:151], v[172:175], v[34:37]
	ds_read_b128 v[148:151], v131 offset:23104
	s_waitcnt lgkmcnt(5)
	v_mfma_f32_16x16x32_bf16 v[30:33], v[152:155], v[160:163], v[30:33]
	v_mfma_f32_16x16x32_bf16 v[26:29], v[152:155], v[164:167], v[26:29]
	v_mfma_f32_16x16x32_bf16 v[22:25], v[152:155], v[168:171], v[22:25]
	v_mfma_f32_16x16x32_bf16 v[18:21], v[152:155], v[172:175], v[18:21]
	ds_read_b128 v[152:155], v131 offset:25664
	s_waitcnt lgkmcnt(5)
	v_mfma_f32_16x16x32_bf16 v[6:9], v[156:159], v[168:171], v[6:9]
	v_mfma_f32_16x16x32_bf16 v[2:5], v[156:159], v[172:175], v[2:5]
	ds_read_b128 v[168:171], v238 offset:5184
	ds_read_b128 v[172:175], v238 offset:7744
	v_mfma_f32_16x16x32_bf16 v[14:17], v[156:159], v[160:163], v[14:17]
	v_mfma_f32_16x16x32_bf16 v[10:13], v[156:159], v[164:167], v[10:13]
	ds_read_b128 v[156:159], v131 offset:28224
	s_waitcnt lgkmcnt(5)
	v_mfma_f32_16x16x32_bf16 v[126:129], v[144:147], v[176:179], v[126:129]
	s_waitcnt lgkmcnt(4)
	v_mfma_f32_16x16x32_bf16 v[110:113], v[148:151], v[176:179], v[110:113]
	s_waitcnt lgkmcnt(3)
	v_mfma_f32_16x16x32_bf16 v[30:33], v[152:155], v[176:179], v[30:33]
	v_mfma_f32_16x16x32_bf16 v[122:125], v[144:147], v[180:183], v[122:125]
	v_mfma_f32_16x16x32_bf16 v[74:77], v[148:151], v[180:183], v[74:77]
	v_mfma_f32_16x16x32_bf16 v[26:29], v[152:155], v[180:183], v[26:29]
	s_waitcnt lgkmcnt(2)
	v_mfma_f32_16x16x32_bf16 v[118:121], v[144:147], v[168:171], v[118:121]
	v_mfma_f32_16x16x32_bf16 v[38:41], v[148:151], v[168:171], v[38:41]
	v_mfma_f32_16x16x32_bf16 v[22:25], v[152:155], v[168:171], v[22:25]
	s_waitcnt lgkmcnt(1)
	v_mfma_f32_16x16x32_bf16 v[114:117], v[144:147], v[172:175], v[114:117]
	v_mfma_f32_16x16x32_bf16 v[34:37], v[148:151], v[172:175], v[34:37]
	v_mfma_f32_16x16x32_bf16 v[18:21], v[152:155], v[172:175], v[18:21]
	s_waitcnt lgkmcnt(0)
	v_mfma_f32_16x16x32_bf16 v[14:17], v[156:159], v[176:179], v[14:17]
	s_barrier
	v_mfma_f32_16x16x32_bf16 v[10:13], v[156:159], v[180:183], v[10:13]
	s_waitcnt vmcnt(8)
	ds_write_b128 v130, v[46:49]
	ds_write_b128 v130, v[54:57] offset:20480
	ds_write_b128 v130, v[62:65] offset:5120
	ds_write_b128 v130, v[70:73] offset:25600
	ds_write_b128 v130, v[82:85] offset:10240
	ds_write_b128 v130, v[90:93] offset:30720
	ds_write_b128 v130, v[98:101] offset:15360
	ds_write_b128 v130, v[106:109] offset:35840
	v_mfma_f32_16x16x32_bf16 v[6:9], v[156:159], v[168:171], v[6:9]
	s_waitcnt lgkmcnt(0)
	v_mfma_f32_16x16x32_bf16 v[2:5], v[156:159], v[172:175], v[2:5]
	s_cbranch_scc1 .LBB0_200
	v_add_co_u32_e32 v46, vcc, 0x4200000, v138
	s_nop 1
	v_addc_co_u32_e32 v47, vcc, 0, v139, vcc
	v_add_co_u32_e32 v54, vcc, 0xb3a0000, v136
	global_load_dwordx4 v[46:49], v[46:47], off offset:384
	s_nop 0
	v_addc_co_u32_e32 v55, vcc, 0, v137, vcc
	v_add_co_u32_e32 v62, vcc, 0x4211000, v138
	global_load_dwordx4 v[54:57], v[54:55], off offset:384
	s_nop 0
	v_addc_co_u32_e32 v63, vcc, 0, v139, vcc
	v_add_co_u32_e32 v70, vcc, 0xb3b1000, v136
	global_load_dwordx4 v[62:65], v[62:63], off offset:384
	s_nop 0
	v_addc_co_u32_e32 v71, vcc, 0, v137, vcc
	v_add_co_u32_e32 v82, vcc, 0x4222000, v138
	global_load_dwordx4 v[70:73], v[70:71], off offset:384
	s_nop 0
	v_addc_co_u32_e32 v83, vcc, 0, v139, vcc
	v_add_co_u32_e32 v90, vcc, 0xb3c2000, v136
	global_load_dwordx4 v[82:85], v[82:83], off offset:384
	s_nop 0
	v_addc_co_u32_e32 v91, vcc, 0, v137, vcc
	v_add_co_u32_e32 v98, vcc, 0x4233000, v138
	global_load_dwordx4 v[90:93], v[90:91], off offset:384
	s_nop 0
	v_addc_co_u32_e32 v99, vcc, 0, v139, vcc
	v_add_co_u32_e32 v106, vcc, 0xb3d3000, v136
	global_load_dwordx4 v[98:101], v[98:99], off offset:384
	s_nop 0
	v_addc_co_u32_e32 v107, vcc, 0, v137, vcc
	global_load_dwordx4 v[106:109], v[106:107], off offset:384
	s_branch .LBB0_200

; DEV f32x4 mfma16(bf16x8 a, bf16x8 b, f32x4 c) { return __builtin_amdgcn_mfma_f32_16x16x32_bf16(a, b, c, 0, 0, 0); }
; #define G_LOAD(RA, RB, KT) { _Pragma("unroll") for (int i = 0; i < 4; i++) { \
;       RA[i] = *(const u32x4*)(Ap + (size_t)(i * 32) * lda + (KT) * 64); RB[i] = *(const u32x4*)(Bp + (size_t)(i * 32) * ldb + (KT) * 64); } }
; #define G_STORE(RA, RB) { _Pragma("unroll") for (int i = 0; i < 4; i++) { \
;       *(u32x4*)(As + (lrow + i * 32) * GLD + lcc * 8) = RA[i]; *(u32x4*)(Bs + (lrow + i * 32) * GLD + lcc * 8) = RB[i]; } }
; template <int TI, int TJ, int KS>
; DEV void mfma_lds(const bf16_t* Arows, int lda, const bf16_t* Brows, int ldb, int i0, int j0, f32x4 (&acc)[TI][TJ]) {
;     ...
;   for (int ks = 0; ks < KS; ks++) {
;     bf16x8 af[TI], bfr[TJ];
; #pragma unroll
;     for (int i = 0; i < TI; i++) af[i] = *(const bf16x8*)(Arows + (i0 + i * 16 + l15) * lda + ks * 32 + quad * 8);
; #pragma unroll
;     for (int j = 0; j < TJ; j++) bfr[j] = *(const bf16x8*)(Brows + (j0 + j * 16 + l15) * ldb + ks * 32 + quad * 8);
; #pragma unroll
;     for (int i = 0; i < TI; i++)
; #pragma unroll
;       for (int j = 0; j < TJ; j++) acc[i][j] = mfma16(af[i], bfr[j], acc[i][j]);
;   }
; template <class Epi>
; DEV void gemm_tile(const bf16_t* __restrict__ A, int lda, const bf16_t* __restrict__ Bt, int ldb, int K, int m0, int n0,
;                    Epi& epi, char* smem) {
;     ...
;   for (int kt = 0; kt < nk; kt += 2) {
;     __syncthreads();
;     G_STORE(ra0, rb0);
;     __syncthreads();
;     if (kt + 2 < nk) G_LOAD(ra0, rb0, kt + 2);
;     mfma_lds<4, 4, 2>(Bs, GLD, As, GLD, wn * 64, wm * 64, acc);
;     __syncthreads();
;     G_STORE(ra1, rb1);
;     __syncthreads();
;     if (kt + 3 < nk) G_LOAD(ra1, rb1, kt + 3);
;     mfma_lds<4, 4, 2>(Bs, GLD, As, GLD, wn * 64, wm * 64, acc);
;   }
.LBB0_324:
	s_barrier
	v_mov_b32_e32 v131, v195
	v_and_b32_e32 v143, 15, v131
	v_or_b32_e32 v144, v143, v142
	v_and_b32_e32 v148, 48, v131
	v_mul_u32_u24_e32 v131, 0x50, v144
	v_lshl_add_u32 v131, v131, 1, v148
	v_or_b32_e32 v143, v143, v141
	v_mad_u32_u24 v238, v143, s36, v148
	v_lshl_add_u64 v[132:133], v[132:133], 0, s[34:35]
	v_lshl_add_u64 v[134:135], v[134:135], 0, s[34:35]
	s_and_b64 vcc, exec, s[6:7]
	ds_read_b128 v[144:147], v131 offset:20480
	ds_read_b128 v[160:163], v238
	ds_read_b128 v[164:167], v238 offset:2560
	ds_read_b128 v[168:171], v238 offset:5120
	ds_read_b128 v[172:175], v238 offset:7680
	ds_read_b128 v[148:151], v131 offset:23040
	ds_read_b128 v[152:155], v131 offset:25600
	ds_read_b128 v[156:159], v131 offset:28160
	ds_read_b128 v[176:179], v238 offset:64
	ds_read_b128 v[180:183], v238 offset:2624
	s_waitcnt lgkmcnt(8)
	v_mfma_f32_16x16x32_bf16 v[62:65], v[144:147], v[160:163], v[62:65]
	s_waitcnt lgkmcnt(7)
	v_mfma_f32_16x16x32_bf16 v[58:61], v[144:147], v[164:167], v[58:61]
	s_waitcnt lgkmcnt(6)
	v_mfma_f32_16x16x32_bf16 v[54:57], v[144:147], v[168:171], v[54:57]
	s_waitcnt lgkmcnt(5)
	v_mfma_f32_16x16x32_bf16 v[50:53], v[144:147], v[172:175], v[50:53]
	ds_read_b128 v[144:147], v131 offset:20544
	s_waitcnt lgkmcnt(5)
	v_mfma_f32_16x16x32_bf16 v[46:49], v[148:151], v[160:163], v[46:49]
	v_mfma_f32_16x16x32_bf16 v[42:45], v[148:151], v[164:167], v[42:45]
	v_mfma_f32_16x16x32_bf16 v[38:41], v[148:151], v[168:171], v[38:41]
	v_mfma_f32_16x16x32_bf16 v[34:37], v[148:151], v[172:175], v[34:37]
	ds_read_b128 v[148:151], v131 offset:23104
	s_waitcnt lgkmcnt(5)
	v_mfma_f32_16x16x32_bf16 v[30:33], v[152:155], v[160:163], v[30:33]
	v_mfma_f32_16x16x32_bf16 v[26:29], v[152:155], v[164:167], v[26:29]
	v_mfma_f32_16x16x32_bf16 v[22:25], v[152:155], v[168:171], v[22:25]
	v_mfma_f32_16x16x32_bf16 v[18:21], v[152:155], v[172:175], v[18:21]
	ds_read_b128 v[152:155], v131 offset:25664
	s_waitcnt lgkmcnt(5)
	v_mfma_f32_16x16x32_bf16 v[6:9], v[156:159], v[168:171], v[6:9]
	v_mfma_f32_16x16x32_bf16 v[2:5], v[156:159], v[172:175], v[2:5]
	ds_read_b128 v[168:171], v238 offset:5184
	ds_read_b128 v[172:175], v238 offset:7744
	v_mfma_f32_16x16x32_bf16 v[14:17], v[156:159], v[160:163], v[14:17]
	v_mfma_f32_16x16x32_bf16 v[10:13], v[156:159], v[164:167], v[10:13]
	ds_read_b128 v[156:159], v131 offset:28224
	s_waitcnt lgkmcnt(5)
	v_mfma_f32_16x16x32_bf16 v[62:65], v[144:147], v[176:179], v[62:65]
	s_waitcnt lgkmcnt(4)
	v_mfma_f32_16x16x32_bf16 v[46:49], v[148:151], v[176:179], v[46:49]
	s_waitcnt lgkmcnt(3)
	v_mfma_f32_16x16x32_bf16 v[30:33], v[152:155], v[176:179], v[30:33]
	v_mfma_f32_16x16x32_bf16 v[58:61], v[144:147], v[180:183], v[58:61]
	v_mfma_f32_16x16x32_bf16 v[42:45], v[148:151], v[180:183], v[42:45]
	v_mfma_f32_16x16x32_bf16 v[26:29], v[152:155], v[180:183], v[26:29]
	s_waitcnt lgkmcnt(2)
	v_mfma_f32_16x16x32_bf16 v[54:57], v[144:147], v[168:171], v[54:57]
	v_mfma_f32_16x16x32_bf16 v[38:41], v[148:151], v[168:171], v[38:41]
	v_mfma_f32_16x16x32_bf16 v[22:25], v[152:155], v[168:171], v[22:25]
	s_waitcnt lgkmcnt(1)
	v_mfma_f32_16x16x32_bf16 v[50:53], v[144:147], v[172:175], v[50:53]
	v_mfma_f32_16x16x32_bf16 v[34:37], v[148:151], v[172:175], v[34:37]
	v_mfma_f32_16x16x32_bf16 v[18:21], v[152:155], v[172:175], v[18:21]
	s_waitcnt lgkmcnt(0)
	v_mfma_f32_16x16x32_bf16 v[14:17], v[156:159], v[176:179], v[14:17]
	v_mfma_f32_16x16x32_bf16 v[10:13], v[156:159], v[180:183], v[10:13]
	v_mfma_f32_16x16x32_bf16 v[6:9], v[156:159], v[168:171], v[6:9]
	v_mfma_f32_16x16x32_bf16 v[2:5], v[156:159], v[172:175], v[2:5]
	s_cbranch_vccnz .LBB0_329
.LBB0_325:
	s_add_i32 s1, s1, 2
	s_cmp_gt_u32 s1, 13
	s_cselect_b64 s[6:7], -1, 0
	s_and_b64 vcc, exec, s[6:7]
	v_lshl_add_u64 v[138:139], v[134:135], 0, v[0:1]
	v_lshl_add_u64 v[136:137], v[132:133], 0, v[0:1]
	s_waitcnt lgkmcnt(0)
	s_barrier
	s_waitcnt vmcnt(8)
	ds_write_b128 v130, v[66:69]
	ds_write_b128 v130, v[74:77] offset:20480
	ds_write_b128 v130, v[82:85] offset:5120
	ds_write_b128 v130, v[90:93] offset:25600
	ds_write_b128 v130, v[98:101] offset:10240
	ds_write_b128 v130, v[106:109] offset:30720
	ds_write_b128 v130, v[114:117] offset:15360
	ds_write_b128 v130, v[122:125] offset:35840
	s_waitcnt lgkmcnt(0)
	s_cbranch_vccnz .Lgw_skip_2
	v_add_co_u32_e32 v66, vcc, 0x4200000, v138
	s_nop 1
	v_addc_co_u32_e32 v67, vcc, 0, v139, vcc
	v_add_co_u32_e32 v74, vcc, 0xa900000, v136
	global_load_dwordx4 v[66:69], v[66:67], off offset:256
	s_nop 0
	v_addc_co_u32_e32 v75, vcc, 0, v137, vcc
	v_add_co_u32_e32 v82, vcc, 0x4211000, v138
	global_load_dwordx4 v[74:77], v[74:75], off offset:256
	s_nop 0
	v_addc_co_u32_e32 v83, vcc, 0, v139, vcc
	v_add_co_u32_e32 v90, vcc, 0xa911000, v136
	global_load_dwordx4 v[82:85], v[82:83], off offset:256
	s_nop 0
	v_addc_co_u32_e32 v91, vcc, 0, v137, vcc
	v_add_co_u32_e32 v98, vcc, 0x4222000, v138
	global_load_dwordx4 v[90:93], v[90:91], off offset:256
	s_nop 0
	v_addc_co_u32_e32 v99, vcc, 0, v139, vcc
	v_add_co_u32_e32 v106, vcc, 0xa922000, v136
	global_load_dwordx4 v[98:101], v[98:99], off offset:256
	s_nop 0
	v_addc_co_u32_e32 v107, vcc, 0, v137, vcc
	v_add_co_u32_e32 v114, vcc, 0x4233000, v138
	global_load_dwordx4 v[106:109], v[106:107], off offset:256
	s_nop 0
	v_addc_co_u32_e32 v115, vcc, 0, v139, vcc
	v_add_co_u32_e32 v122, vcc, 0xa933000, v136
	global_load_dwordx4 v[114:117], v[114:115], off offset:256
	s_nop 0
	v_addc_co_u32_e32 v123, vcc, 0, v137, vcc
	global_load_dwordx4 v[122:125], v[122:123], off offset:256
; DEV f32x4 mfma16(bf16x8 a, bf16x8 b, f32x4 c) { return __builtin_amdgcn_mfma_f32_16x16x32_bf16(a, b, c, 0, 0, 0); }
; #define G_LOAD(RA, RB, KT) { _Pragma("unroll") for (int i = 0; i < 4; i++) { \
;       RA[i] = *(const u32x4*)(Ap + (size_t)(i * 32) * lda + (KT) * 64); RB[i] = *(const u32x4*)(Bp + (size_t)(i * 32) * ldb + (KT) * 64); } }
; #define G_STORE(RA, RB) { _Pragma("unroll") for (int i = 0; i < 4; i++) { \
;       *(u32x4*)(As + (lrow + i * 32) * GLD + lcc * 8) = RA[i]; *(u32x4*)(Bs + (lrow + i * 32) * GLD + lcc * 8) = RB[i]; } }
; template <int TI, int TJ, int KS>
; DEV void mfma_lds(const bf16_t* Arows, int lda, const bf16_t* Brows, int ldb, int i0, int j0, f32x4 (&acc)[TI][TJ]) {
;     ...
;   for (int ks = 0; ks < KS; ks++) {
;     bf16x8 af[TI], bfr[TJ];
; #pragma unroll
;     for (int i = 0; i < TI; i++) af[i] = *(const bf16x8*)(Arows + (i0 + i * 16 + l15) * lda + ks * 32 + quad * 8);
; #pragma unroll
;     for (int j = 0; j < TJ; j++) bfr[j] = *(const bf16x8*)(Brows + (j0 + j * 16 + l15) * ldb + ks * 32 + quad * 8);
; #pragma unroll
;     for (int i = 0; i < TI; i++)
; #pragma unroll
;       for (int j = 0; j < TJ; j++) acc[i][j] = mfma16(af[i], bfr[j], acc[i][j]);
;   }
; template <class Epi>
; DEV void gemm_tile(const bf16_t* __restrict__ A, int lda, const bf16_t* __restrict__ Bt, int ldb, int K, int m0, int n0,
;                    Epi& epi, char* smem) {
;     ...
;   for (int kt = 0; kt < nk; kt += 2) {
;     __syncthreads();
;     G_STORE(ra0, rb0);
;     __syncthreads();
;     if (kt + 2 < nk) G_LOAD(ra0, rb0, kt + 2);
;     mfma_lds<4, 4, 2>(Bs, GLD, As, GLD, wn * 64, wm * 64, acc);
;     __syncthreads();
;     G_STORE(ra1, rb1);
;     __syncthreads();
;     if (kt + 3 < nk) G_LOAD(ra1, rb1, kt + 3);
;     mfma_lds<4, 4, 2>(Bs, GLD, As, GLD, wn * 64, wm * 64, acc);
;   }
.LBB0_327:
	s_barrier
	v_mov_b32_e32 v131, v195
	s_cmp_gt_u32 s1, 12
	v_and_b32_e32 v143, 15, v131
	v_or_b32_e32 v144, v143, v142
	v_and_b32_e32 v148, 48, v131
	v_mul_u32_u24_e32 v131, 0x50, v144
	v_lshl_add_u32 v131, v131, 1, v148
	v_or_b32_e32 v143, v143, v141
	v_mad_u32_u24 v238, v143, s36, v148
	ds_read_b128 v[144:147], v131 offset:20480
	ds_read_b128 v[160:163], v238
	ds_read_b128 v[164:167], v238 offset:2560
	ds_read_b128 v[168:171], v238 offset:5120
	ds_read_b128 v[172:175], v238 offset:7680
	ds_read_b128 v[148:151], v131 offset:23040
	ds_read_b128 v[152:155], v131 offset:25600
	ds_read_b128 v[156:159], v131 offset:28160
	ds_read_b128 v[176:179], v238 offset:64
	ds_read_b128 v[180:183], v238 offset:2624
	s_waitcnt lgkmcnt(8)
	v_mfma_f32_16x16x32_bf16 v[62:65], v[144:147], v[160:163], v[62:65]
	s_waitcnt lgkmcnt(7)
	v_mfma_f32_16x16x32_bf16 v[58:61], v[144:147], v[164:167], v[58:61]
	s_waitcnt lgkmcnt(6)
	v_mfma_f32_16x16x32_bf16 v[54:57], v[144:147], v[168:171], v[54:57]
	s_waitcnt lgkmcnt(5)
	v_mfma_f32_16x16x32_bf16 v[50:53], v[144:147], v[172:175], v[50:53]
	ds_read_b128 v[144:147], v131 offset:20544
	s_waitcnt lgkmcnt(5)
	v_mfma_f32_16x16x32_bf16 v[46:49], v[148:151], v[160:163], v[46:49]
	v_mfma_f32_16x16x32_bf16 v[42:45], v[148:151], v[164:167], v[42:45]
	v_mfma_f32_16x16x32_bf16 v[38:41], v[148:151], v[168:171], v[38:41]
	v_mfma_f32_16x16x32_bf16 v[34:37], v[148:151], v[172:175], v[34:37]
	ds_read_b128 v[148:151], v131 offset:23104
	s_waitcnt lgkmcnt(5)
	v_mfma_f32_16x16x32_bf16 v[30:33], v[152:155], v[160:163], v[30:33]
	v_mfma_f32_16x16x32_bf16 v[26:29], v[152:155], v[164:167], v[26:29]
	v_mfma_f32_16x16x32_bf16 v[22:25], v[152:155], v[168:171], v[22:25]
	v_mfma_f32_16x16x32_bf16 v[18:21], v[152:155], v[172:175], v[18:21]
	ds_read_b128 v[152:155], v131 offset:25664
	s_waitcnt lgkmcnt(5)
	v_mfma_f32_16x16x32_bf16 v[6:9], v[156:159], v[168:171], v[6:9]
	v_mfma_f32_16x16x32_bf16 v[2:5], v[156:159], v[172:175], v[2:5]
	ds_read_b128 v[168:171], v238 offset:5184
	ds_read_b128 v[172:175], v238 offset:7744
	v_mfma_f32_16x16x32_bf16 v[14:17], v[156:159], v[160:163], v[14:17]
	v_mfma_f32_16x16x32_bf16 v[10:13], v[156:159], v[164:167], v[10:13]
	ds_read_b128 v[156:159], v131 offset:28224
	s_waitcnt lgkmcnt(5)
	v_mfma_f32_16x16x32_bf16 v[62:65], v[144:147], v[176:179], v[62:65]
	s_waitcnt lgkmcnt(4)
	v_mfma_f32_16x16x32_bf16 v[46:49], v[148:151], v[176:179], v[46:49]
	s_waitcnt lgkmcnt(3)
	v_mfma_f32_16x16x32_bf16 v[30:33], v[152:155], v[176:179], v[30:33]
	v_mfma_f32_16x16x32_bf16 v[58:61], v[144:147], v[180:183], v[58:61]
	v_mfma_f32_16x16x32_bf16 v[42:45], v[148:151], v[180:183], v[42:45]
	v_mfma_f32_16x16x32_bf16 v[26:29], v[152:155], v[180:183], v[26:29]
	s_waitcnt lgkmcnt(2)
	v_mfma_f32_16x16x32_bf16 v[54:57], v[144:147], v[168:171], v[54:57]
	v_mfma_f32_16x16x32_bf16 v[38:41], v[148:151], v[168:171], v[38:41]
	v_mfma_f32_16x16x32_bf16 v[22:25], v[152:155], v[168:171], v[22:25]
	s_waitcnt lgkmcnt(1)
	v_mfma_f32_16x16x32_bf16 v[50:53], v[144:147], v[172:175], v[50:53]
	v_mfma_f32_16x16x32_bf16 v[34:37], v[148:151], v[172:175], v[34:37]
	v_mfma_f32_16x16x32_bf16 v[18:21], v[152:155], v[172:175], v[18:21]
	s_waitcnt lgkmcnt(0)
	v_mfma_f32_16x16x32_bf16 v[14:17], v[156:159], v[176:179], v[14:17]
	s_barrier
	v_mfma_f32_16x16x32_bf16 v[10:13], v[156:159], v[180:183], v[10:13]
	s_waitcnt vmcnt(8)
	ds_write_b128 v130, v[70:73]
	ds_write_b128 v130, v[78:81] offset:20480
	ds_write_b128 v130, v[86:89] offset:5120
	ds_write_b128 v130, v[94:97] offset:25600
	ds_write_b128 v130, v[102:105] offset:10240
	ds_write_b128 v130, v[110:113] offset:30720
	ds_write_b128 v130, v[118:121] offset:15360
	ds_write_b128 v130, v[126:129] offset:35840
	v_mfma_f32_16x16x32_bf16 v[6:9], v[156:159], v[168:171], v[6:9]
	s_waitcnt lgkmcnt(0)
	v_mfma_f32_16x16x32_bf16 v[2:5], v[156:159], v[172:175], v[2:5]
	s_cbranch_scc1 .LBB0_324
	v_add_co_u32_e32 v70, vcc, 0x4200000, v138
	s_nop 1
	v_addc_co_u32_e32 v71, vcc, 0, v139, vcc
	v_add_co_u32_e32 v78, vcc, 0xa900000, v136
	global_load_dwordx4 v[70:73], v[70:71], off offset:384
	s_nop 0
	v_addc_co_u32_e32 v79, vcc, 0, v137, vcc
	v_add_co_u32_e32 v86, vcc, 0x4211000, v138
	global_load_dwordx4 v[78:81], v[78:79], off offset:384
	s_nop 0
	v_addc_co_u32_e32 v87, vcc, 0, v139, vcc
	v_add_co_u32_e32 v94, vcc, 0xa911000, v136
	global_load_dwordx4 v[86:89], v[86:87], off offset:384
	s_nop 0
	v_addc_co_u32_e32 v95, vcc, 0, v137, vcc
	v_add_co_u32_e32 v102, vcc, 0x4222000, v138
	global_load_dwordx4 v[94:97], v[94:95], off offset:384
	s_nop 0
	v_addc_co_u32_e32 v103, vcc, 0, v139, vcc
	v_add_co_u32_e32 v110, vcc, 0xa922000, v136
	global_load_dwordx4 v[102:105], v[102:103], off offset:384
	s_nop 0
	v_addc_co_u32_e32 v111, vcc, 0, v137, vcc
	v_add_co_u32_e32 v118, vcc, 0x4233000, v138
	global_load_dwordx4 v[110:113], v[110:111], off offset:384
	s_nop 0
	v_addc_co_u32_e32 v119, vcc, 0, v139, vcc
	v_add_co_u32_e32 v126, vcc, 0xa933000, v136
	global_load_dwordx4 v[118:121], v[118:119], off offset:384
	s_nop 0
	v_addc_co_u32_e32 v127, vcc, 0, v137, vcc
	global_load_dwordx4 v[126:129], v[126:127], off offset:384
	s_branch .LBB0_324

; DEV f32x4 mfma16(bf16x8 a, bf16x8 b, f32x4 c) { return __builtin_amdgcn_mfma_f32_16x16x32_bf16(a, b, c, 0, 0, 0); }
; #define G_LOAD(RA, RB, KT) { _Pragma("unroll") for (int i = 0; i < 4; i++) { \
;       RA[i] = *(const u32x4*)(Ap + (size_t)(i * 32) * lda + (KT) * 64); RB[i] = *(const u32x4*)(Bp + (size_t)(i * 32) * ldb + (KT) * 64); } }
; #define G_STORE(RA, RB) { _Pragma("unroll") for (int i = 0; i < 4; i++) { \
;       *(u32x4*)(As + (lrow + i * 32) * GLD + lcc * 8) = RA[i]; *(u32x4*)(Bs + (lrow + i * 32) * GLD + lcc * 8) = RB[i]; } }
; template <int TI, int TJ, int KS>
; DEV void mfma_lds(const bf16_t* Arows, int lda, const bf16_t* Brows, int ldb, int i0, int j0, f32x4 (&acc)[TI][TJ]) {
;     ...
;   for (int ks = 0; ks < KS; ks++) {
;     bf16x8 af[TI], bfr[TJ];
; #pragma unroll
;     for (int i = 0; i < TI; i++) af[i] = *(const bf16x8*)(Arows + (i0 + i * 16 + l15) * lda + ks * 32 + quad * 8);
; #pragma unroll
;     for (int j = 0; j < TJ; j++) bfr[j] = *(const bf16x8*)(Brows + (j0 + j * 16 + l15) * ldb + ks * 32 + quad * 8);
; #pragma unroll
;     for (int i = 0; i < TI; i++)
; #pragma unroll
;       for (int j = 0; j < TJ; j++) acc[i][j] = mfma16(af[i], bfr[j], acc[i][j]);
;   }
; template <class Epi>
; DEV void gemm_tile(const bf16_t* __restrict__ A, int lda, const bf16_t* __restrict__ Bt, int ldb, int K, int m0, int n0,
;                    Epi& epi, char* smem) {
;     ...
;   for (int kt = 0; kt < nk; kt += 2) {
;     __syncthreads();
;     G_STORE(ra0, rb0);
;     __syncthreads();
;     if (kt + 2 < nk) G_LOAD(ra0, rb0, kt + 2);
;     mfma_lds<4, 4, 2>(Bs, GLD, As, GLD, wn * 64, wm * 64, acc);
;     __syncthreads();
;     G_STORE(ra1, rb1);
;     __syncthreads();
;     if (kt + 3 < nk) G_LOAD(ra1, rb1, kt + 3);
;     mfma_lds<4, 4, 2>(Bs, GLD, As, GLD, wn * 64, wm * 64, acc);
;   }
.LBB0_646:
	s_barrier
	v_mov_b32_e32 v130, v195
	v_and_b32_e32 v135, 15, v130
	v_or_b32_e32 v131, v135, v144
	v_and_b32_e32 v148, 48, v130
	v_mul_u32_u24_e32 v130, 0x50, v131
	v_lshl_add_u32 v147, v130, 1, v148
	v_or_b32_e32 v135, v135, v146
	v_mad_u32_u24 v238, v135, s36, v148
	v_lshl_add_u64 v[136:137], v[136:137], 0, s[34:35]
	v_lshl_add_u64 v[138:139], v[138:139], 0, s[34:35]
	s_andn2_b64 vcc, exec, s[8:9]
	ds_read_b128 v[148:151], v147 offset:20480
	ds_read_b128 v[164:167], v238
	ds_read_b128 v[168:171], v238 offset:2560
	ds_read_b128 v[172:175], v238 offset:5120
	ds_read_b128 v[176:179], v238 offset:7680
	ds_read_b128 v[152:155], v147 offset:23040
	ds_read_b128 v[156:159], v147 offset:25600
	ds_read_b128 v[160:163], v147 offset:28160
	ds_read_b128 v[180:183], v238 offset:64
	ds_read_b128 v[184:187], v238 offset:2624
	s_waitcnt lgkmcnt(8)
	v_mfma_f32_16x16x32_bf16 v[106:109], v[148:151], v[164:167], v[106:109]
	s_waitcnt lgkmcnt(7)
	v_mfma_f32_16x16x32_bf16 v[122:125], v[148:151], v[168:171], v[122:125]
	s_waitcnt lgkmcnt(6)
	v_mfma_f32_16x16x32_bf16 v[114:117], v[148:151], v[172:175], v[114:117]
	s_waitcnt lgkmcnt(5)
	v_mfma_f32_16x16x32_bf16 v[110:113], v[148:151], v[176:179], v[110:113]
	ds_read_b128 v[148:151], v147 offset:20544
	s_waitcnt lgkmcnt(5)
	v_mfma_f32_16x16x32_bf16 v[102:105], v[152:155], v[164:167], v[102:105]
	v_mfma_f32_16x16x32_bf16 v[94:97], v[152:155], v[168:171], v[94:97]
	v_mfma_f32_16x16x32_bf16 v[86:89], v[152:155], v[172:175], v[86:89]
	v_mfma_f32_16x16x32_bf16 v[78:81], v[152:155], v[176:179], v[78:81]
	ds_read_b128 v[152:155], v147 offset:23104
	s_waitcnt lgkmcnt(5)
	v_mfma_f32_16x16x32_bf16 v[82:85], v[156:159], v[164:167], v[82:85]
	v_mfma_f32_16x16x32_bf16 v[74:77], v[156:159], v[168:171], v[74:77]
	v_mfma_f32_16x16x32_bf16 v[70:73], v[156:159], v[172:175], v[70:73]
	v_mfma_f32_16x16x32_bf16 v[66:69], v[156:159], v[176:179], v[66:69]
	ds_read_b128 v[156:159], v147 offset:25664
	s_waitcnt lgkmcnt(5)
	v_mfma_f32_16x16x32_bf16 v[126:129], v[160:163], v[172:175], v[126:129]
	v_mfma_f32_16x16x32_bf16 v[118:121], v[160:163], v[176:179], v[118:121]
	ds_read_b128 v[172:175], v238 offset:5184
	ds_read_b128 v[176:179], v238 offset:7744
	v_mfma_f32_16x16x32_bf16 v[98:101], v[160:163], v[164:167], v[98:101]
	v_mfma_f32_16x16x32_bf16 v[90:93], v[160:163], v[168:171], v[90:93]
	ds_read_b128 v[160:163], v147 offset:28224
	s_waitcnt lgkmcnt(5)
	v_mfma_f32_16x16x32_bf16 v[106:109], v[148:151], v[180:183], v[106:109]
	s_waitcnt lgkmcnt(4)
	v_mfma_f32_16x16x32_bf16 v[102:105], v[152:155], v[180:183], v[102:105]
	s_waitcnt lgkmcnt(3)
	v_mfma_f32_16x16x32_bf16 v[82:85], v[156:159], v[180:183], v[82:85]
	v_mfma_f32_16x16x32_bf16 v[122:125], v[148:151], v[184:187], v[122:125]
	v_mfma_f32_16x16x32_bf16 v[94:97], v[152:155], v[184:187], v[94:97]
	v_mfma_f32_16x16x32_bf16 v[74:77], v[156:159], v[184:187], v[74:77]
	s_waitcnt lgkmcnt(2)
	v_mfma_f32_16x16x32_bf16 v[114:117], v[148:151], v[172:175], v[114:117]
	v_mfma_f32_16x16x32_bf16 v[86:89], v[152:155], v[172:175], v[86:89]
	v_mfma_f32_16x16x32_bf16 v[70:73], v[156:159], v[172:175], v[70:73]
	s_waitcnt lgkmcnt(1)
	v_mfma_f32_16x16x32_bf16 v[110:113], v[148:151], v[176:179], v[110:113]
	v_mfma_f32_16x16x32_bf16 v[78:81], v[152:155], v[176:179], v[78:81]
	v_mfma_f32_16x16x32_bf16 v[66:69], v[156:159], v[176:179], v[66:69]
	s_waitcnt lgkmcnt(0)
	v_mfma_f32_16x16x32_bf16 v[98:101], v[160:163], v[180:183], v[98:101]
	v_mfma_f32_16x16x32_bf16 v[90:93], v[160:163], v[184:187], v[90:93]
	v_mfma_f32_16x16x32_bf16 v[126:129], v[160:163], v[172:175], v[126:129]
	v_mfma_f32_16x16x32_bf16 v[118:121], v[160:163], v[176:179], v[118:121]
	s_cbranch_vccz .LBB0_642
.LBB0_647:
	s_add_i32 s14, s14, 2
	s_cmp_gt_u32 s14, 13
	s_cselect_b64 s[8:9], -1, 0
	s_and_b64 vcc, exec, s[8:9]
	v_lshl_add_u64 v[142:143], v[138:139], 0, v[0:1]
	v_lshl_add_u64 v[140:141], v[136:137], 0, v[0:1]
	s_waitcnt lgkmcnt(0)
	s_barrier
	s_waitcnt vmcnt(8)
	ds_write_b128 v134, v[2:5]
	ds_write_b128 v134, v[10:13] offset:20480
	ds_write_b128 v134, v[18:21] offset:5120
	ds_write_b128 v134, v[26:29] offset:25600
	ds_write_b128 v134, v[34:37] offset:10240
	ds_write_b128 v134, v[42:45] offset:30720
	ds_write_b128 v134, v[50:53] offset:15360
	ds_write_b128 v134, v[58:61] offset:35840
	s_waitcnt lgkmcnt(0)
	s_cbranch_vccnz .Lgw_skip_3
	v_add_co_u32_e32 v2, vcc, 0x4200000, v142
	s_nop 1
	v_addc_co_u32_e32 v3, vcc, 0, v143, vcc
	v_add_co_u32_e32 v10, vcc, 0xb5c0000, v140
	global_load_dwordx4 v[2:5], v[2:3], off offset:256
	s_nop 0
	v_addc_co_u32_e32 v11, vcc, 0, v141, vcc
	v_add_co_u32_e32 v18, vcc, 0x4211000, v142
	global_load_dwordx4 v[10:13], v[10:11], off offset:256
	s_nop 0
	v_addc_co_u32_e32 v19, vcc, 0, v143, vcc
	v_add_co_u32_e32 v26, vcc, 0xb5d1000, v140
	global_load_dwordx4 v[18:21], v[18:19], off offset:256
	s_nop 0
	v_addc_co_u32_e32 v27, vcc, 0, v141, vcc
	v_add_co_u32_e32 v34, vcc, 0x4222000, v142
	global_load_dwordx4 v[26:29], v[26:27], off offset:256
	s_nop 0
	v_addc_co_u32_e32 v35, vcc, 0, v143, vcc
	v_add_co_u32_e32 v42, vcc, 0xb5e2000, v140
	global_load_dwordx4 v[34:37], v[34:35], off offset:256
	s_nop 0
	v_addc_co_u32_e32 v43, vcc, 0, v141, vcc
	v_add_co_u32_e32 v50, vcc, 0x4233000, v142
	global_load_dwordx4 v[42:45], v[42:43], off offset:256
	s_nop 0
	v_addc_co_u32_e32 v51, vcc, 0, v143, vcc
	v_add_co_u32_e32 v58, vcc, 0xb5f3000, v140
	global_load_dwordx4 v[50:53], v[50:51], off offset:256
	s_nop 0
	v_addc_co_u32_e32 v59, vcc, 0, v141, vcc
	global_load_dwordx4 v[58:61], v[58:59], off offset:256
; DEV f32x4 mfma16(bf16x8 a, bf16x8 b, f32x4 c) { return __builtin_amdgcn_mfma_f32_16x16x32_bf16(a, b, c, 0, 0, 0); }
; #define G_LOAD(RA, RB, KT) { _Pragma("unroll") for (int i = 0; i < 4; i++) { \
;       RA[i] = *(const u32x4*)(Ap + (size_t)(i * 32) * lda + (KT) * 64); RB[i] = *(const u32x4*)(Bp + (size_t)(i * 32) * ldb + (KT) * 64); } }
; #define G_STORE(RA, RB) { _Pragma("unroll") for (int i = 0; i < 4; i++) { \
;       *(u32x4*)(As + (lrow + i * 32) * GLD + lcc * 8) = RA[i]; *(u32x4*)(Bs + (lrow + i * 32) * GLD + lcc * 8) = RB[i]; } }
; template <int TI, int TJ, int KS>
; DEV void mfma_lds(const bf16_t* Arows, int lda, const bf16_t* Brows, int ldb, int i0, int j0, f32x4 (&acc)[TI][TJ]) {
;     ...
;   for (int ks = 0; ks < KS; ks++) {
;     bf16x8 af[TI], bfr[TJ];
; #pragma unroll
;     for (int i = 0; i < TI; i++) af[i] = *(const bf16x8*)(Arows + (i0 + i * 16 + l15) * lda + ks * 32 + quad * 8);
; #pragma unroll
;     for (int j = 0; j < TJ; j++) bfr[j] = *(const bf16x8*)(Brows + (j0 + j * 16 + l15) * ldb + ks * 32 + quad * 8);
; #pragma unroll
;     for (int i = 0; i < TI; i++)
; #pragma unroll
;       for (int j = 0; j < TJ; j++) acc[i][j] = mfma16(af[i], bfr[j], acc[i][j]);
;   }
; template <class Epi>
; DEV void gemm_tile(const bf16_t* __restrict__ A, int lda, const bf16_t* __restrict__ Bt, int ldb, int K, int m0, int n0,
;                    Epi& epi, char* smem) {
;     ...
;   for (int kt = 0; kt < nk; kt += 2) {
;     __syncthreads();
;     G_STORE(ra0, rb0);
;     __syncthreads();
;     if (kt + 2 < nk) G_LOAD(ra0, rb0, kt + 2);
;     mfma_lds<4, 4, 2>(Bs, GLD, As, GLD, wn * 64, wm * 64, acc);
;     __syncthreads();
;     G_STORE(ra1, rb1);
;     __syncthreads();
;     if (kt + 3 < nk) G_LOAD(ra1, rb1, kt + 3);
;     mfma_lds<4, 4, 2>(Bs, GLD, As, GLD, wn * 64, wm * 64, acc);
;   }
.LBB0_649:
	s_barrier
	v_mov_b32_e32 v130, v195
	s_cmp_gt_u32 s14, 12
	v_and_b32_e32 v135, 15, v130
	v_or_b32_e32 v131, v135, v144
	v_and_b32_e32 v148, 48, v130
	v_mul_u32_u24_e32 v130, 0x50, v131
	v_lshl_add_u32 v147, v130, 1, v148
	v_or_b32_e32 v135, v135, v146
	v_mad_u32_u24 v238, v135, s36, v148
	ds_read_b128 v[148:151], v147 offset:20480
	ds_read_b128 v[164:167], v238
	ds_read_b128 v[168:171], v238 offset:2560
	ds_read_b128 v[172:175], v238 offset:5120
	ds_read_b128 v[176:179], v238 offset:7680
	ds_read_b128 v[152:155], v147 offset:23040
	ds_read_b128 v[156:159], v147 offset:25600
	ds_read_b128 v[160:163], v147 offset:28160
	ds_read_b128 v[180:183], v238 offset:64
	ds_read_b128 v[184:187], v238 offset:2624
	s_waitcnt lgkmcnt(8)
	v_mfma_f32_16x16x32_bf16 v[106:109], v[148:151], v[164:167], v[106:109]
	s_waitcnt lgkmcnt(7)
	v_mfma_f32_16x16x32_bf16 v[122:125], v[148:151], v[168:171], v[122:125]
	s_waitcnt lgkmcnt(6)
	v_mfma_f32_16x16x32_bf16 v[114:117], v[148:151], v[172:175], v[114:117]
	s_waitcnt lgkmcnt(5)
	v_mfma_f32_16x16x32_bf16 v[110:113], v[148:151], v[176:179], v[110:113]
	ds_read_b128 v[148:151], v147 offset:20544
	s_waitcnt lgkmcnt(5)
	v_mfma_f32_16x16x32_bf16 v[102:105], v[152:155], v[164:167], v[102:105]
	v_mfma_f32_16x16x32_bf16 v[94:97], v[152:155], v[168:171], v[94:97]
	v_mfma_f32_16x16x32_bf16 v[86:89], v[152:155], v[172:175], v[86:89]
	v_mfma_f32_16x16x32_bf16 v[78:81], v[152:155], v[176:179], v[78:81]
	ds_read_b128 v[152:155], v147 offset:23104
	s_waitcnt lgkmcnt(5)
	v_mfma_f32_16x16x32_bf16 v[82:85], v[156:159], v[164:167], v[82:85]
	v_mfma_f32_16x16x32_bf16 v[74:77], v[156:159], v[168:171], v[74:77]
	v_mfma_f32_16x16x32_bf16 v[70:73], v[156:159], v[172:175], v[70:73]
	v_mfma_f32_16x16x32_bf16 v[66:69], v[156:159], v[176:179], v[66:69]
	ds_read_b128 v[156:159], v147 offset:25664
	s_waitcnt lgkmcnt(5)
	v_mfma_f32_16x16x32_bf16 v[126:129], v[160:163], v[172:175], v[126:129]
	v_mfma_f32_16x16x32_bf16 v[118:121], v[160:163], v[176:179], v[118:121]
	ds_read_b128 v[172:175], v238 offset:5184
	ds_read_b128 v[176:179], v238 offset:7744
	v_mfma_f32_16x16x32_bf16 v[98:101], v[160:163], v[164:167], v[98:101]
	v_mfma_f32_16x16x32_bf16 v[90:93], v[160:163], v[168:171], v[90:93]
	ds_read_b128 v[160:163], v147 offset:28224
	s_waitcnt lgkmcnt(5)
	v_mfma_f32_16x16x32_bf16 v[106:109], v[148:151], v[180:183], v[106:109]
	s_waitcnt lgkmcnt(4)
	v_mfma_f32_16x16x32_bf16 v[102:105], v[152:155], v[180:183], v[102:105]
	s_waitcnt lgkmcnt(3)
	v_mfma_f32_16x16x32_bf16 v[82:85], v[156:159], v[180:183], v[82:85]
	v_mfma_f32_16x16x32_bf16 v[122:125], v[148:151], v[184:187], v[122:125]
	v_mfma_f32_16x16x32_bf16 v[94:97], v[152:155], v[184:187], v[94:97]
	v_mfma_f32_16x16x32_bf16 v[74:77], v[156:159], v[184:187], v[74:77]
	s_waitcnt lgkmcnt(2)
	v_mfma_f32_16x16x32_bf16 v[114:117], v[148:151], v[172:175], v[114:117]
	v_mfma_f32_16x16x32_bf16 v[86:89], v[152:155], v[172:175], v[86:89]
	v_mfma_f32_16x16x32_bf16 v[70:73], v[156:159], v[172:175], v[70:73]
	s_waitcnt lgkmcnt(1)
	v_mfma_f32_16x16x32_bf16 v[110:113], v[148:151], v[176:179], v[110:113]
	v_mfma_f32_16x16x32_bf16 v[78:81], v[152:155], v[176:179], v[78:81]
	v_mfma_f32_16x16x32_bf16 v[66:69], v[156:159], v[176:179], v[66:69]
	s_waitcnt lgkmcnt(0)
	v_mfma_f32_16x16x32_bf16 v[98:101], v[160:163], v[180:183], v[98:101]
	s_barrier
	v_mfma_f32_16x16x32_bf16 v[90:93], v[160:163], v[184:187], v[90:93]
	s_waitcnt vmcnt(8)
	ds_write_b128 v134, v[6:9]
	ds_write_b128 v134, v[14:17] offset:20480
	ds_write_b128 v134, v[22:25] offset:5120
	ds_write_b128 v134, v[30:33] offset:25600
	ds_write_b128 v134, v[38:41] offset:10240
	ds_write_b128 v134, v[46:49] offset:30720
	ds_write_b128 v134, v[54:57] offset:15360
	ds_write_b128 v134, v[62:65] offset:35840
	v_mfma_f32_16x16x32_bf16 v[126:129], v[160:163], v[172:175], v[126:129]
	s_waitcnt lgkmcnt(0)
	v_mfma_f32_16x16x32_bf16 v[118:121], v[160:163], v[176:179], v[118:121]
	s_cbranch_scc1 .LBB0_646
	v_add_co_u32_e32 v6, vcc, 0x4200000, v142
	s_nop 1
	v_addc_co_u32_e32 v7, vcc, 0, v143, vcc
	v_add_co_u32_e32 v14, vcc, 0xb5c0000, v140
	global_load_dwordx4 v[6:9], v[6:7], off offset:384
	s_nop 0
	v_addc_co_u32_e32 v15, vcc, 0, v141, vcc
	v_add_co_u32_e32 v22, vcc, 0x4211000, v142
	global_load_dwordx4 v[14:17], v[14:15], off offset:384
	s_nop 0
	v_addc_co_u32_e32 v23, vcc, 0, v143, vcc
	v_add_co_u32_e32 v30, vcc, 0xb5d1000, v140
	global_load_dwordx4 v[22:25], v[22:23], off offset:384
	s_nop 0
	v_addc_co_u32_e32 v31, vcc, 0, v141, vcc
	v_add_co_u32_e32 v38, vcc, 0x4222000, v142
	global_load_dwordx4 v[30:33], v[30:31], off offset:384
	s_nop 0
	v_addc_co_u32_e32 v39, vcc, 0, v143, vcc
	v_add_co_u32_e32 v46, vcc, 0xb5e2000, v140
	global_load_dwordx4 v[38:41], v[38:39], off offset:384
	s_nop 0
	v_addc_co_u32_e32 v47, vcc, 0, v141, vcc
	v_add_co_u32_e32 v54, vcc, 0x4233000, v142
	global_load_dwordx4 v[46:49], v[46:47], off offset:384
	s_nop 0
	v_addc_co_u32_e32 v55, vcc, 0, v143, vcc
	v_add_co_u32_e32 v62, vcc, 0xb5f3000, v140
	global_load_dwordx4 v[54:57], v[54:55], off offset:384
	s_nop 0
	v_addc_co_u32_e32 v63, vcc, 0, v141, vcc
	global_load_dwordx4 v[62:65], v[62:63], off offset:384
	s_branch .LBB0_646

; DEV f32x4 mfma16(bf16x8 a, bf16x8 b, f32x4 c) { return __builtin_amdgcn_mfma_f32_16x16x32_bf16(a, b, c, 0, 0, 0); }
; #define G_LOAD(RA, RB, KT) { _Pragma("unroll") for (int i = 0; i < 4; i++) { \
;       RA[i] = *(const u32x4*)(Ap + (size_t)(i * 32) * lda + (KT) * 64); RB[i] = *(const u32x4*)(Bp + (size_t)(i * 32) * ldb + (KT) * 64); } }
; #define G_STORE(RA, RB) { _Pragma("unroll") for (int i = 0; i < 4; i++) { \
;       *(u32x4*)(As + (lrow + i * 32) * GLD + lcc * 8) = RA[i]; *(u32x4*)(Bs + (lrow + i * 32) * GLD + lcc * 8) = RB[i]; } }
; template <int TI, int TJ, int KS>
; DEV void mfma_lds(const bf16_t* Arows, int lda, const bf16_t* Brows, int ldb, int i0, int j0, f32x4 (&acc)[TI][TJ]) {
;     ...
;   for (int ks = 0; ks < KS; ks++) {
;     bf16x8 af[TI], bfr[TJ];
; #pragma unroll
;     for (int i = 0; i < TI; i++) af[i] = *(const bf16x8*)(Arows + (i0 + i * 16 + l15) * lda + ks * 32 + quad * 8);
; #pragma unroll
;     for (int j = 0; j < TJ; j++) bfr[j] = *(const bf16x8*)(Brows + (j0 + j * 16 + l15) * ldb + ks * 32 + quad * 8);
; #pragma unroll
;     for (int i = 0; i < TI; i++)
; #pragma unroll
;       for (int j = 0; j < TJ; j++) acc[i][j] = mfma16(af[i], bfr[j], acc[i][j]);
;   }
; template <class Epi>
; DEV void gemm_tile(const bf16_t* __restrict__ A, int lda, const bf16_t* __restrict__ Bt, int ldb, int K, int m0, int n0,
;                    Epi& epi, char* smem) {
;     ...
;   for (int kt = 0; kt < nk; kt += 2) {
;     __syncthreads();
;     G_STORE(ra0, rb0);
;     __syncthreads();
;     if (kt + 2 < nk) G_LOAD(ra0, rb0, kt + 2);
;     mfma_lds<4, 4, 2>(Bs, GLD, As, GLD, wn * 64, wm * 64, acc);
;     __syncthreads();
;     G_STORE(ra1, rb1);
;     __syncthreads();
;     if (kt + 3 < nk) G_LOAD(ra1, rb1, kt + 3);
;     mfma_lds<4, 4, 2>(Bs, GLD, As, GLD, wn * 64, wm * 64, acc);
;   }
.LBB0_670:
	s_barrier
	v_mov_b32_e32 v131, v195
	v_and_b32_e32 v143, 15, v131
	v_or_b32_e32 v144, v143, v140
	v_and_b32_e32 v148, 48, v131
	v_mul_u32_u24_e32 v131, 0x50, v144
	v_lshl_add_u32 v131, v131, 1, v148
	v_or_b32_e32 v143, v143, v142
	v_mad_u32_u24 v238, v143, s36, v148
	v_lshl_add_u64 v[132:133], v[132:133], 0, s[34:35]
	v_lshl_add_u64 v[134:135], v[134:135], 0, s[34:35]
	s_and_b64 vcc, exec, s[8:9]
	ds_read_b128 v[144:147], v131 offset:20480
	ds_read_b128 v[160:163], v238
	ds_read_b128 v[164:167], v238 offset:2560
	ds_read_b128 v[168:171], v238 offset:5120
	ds_read_b128 v[172:175], v238 offset:7680
	ds_read_b128 v[148:151], v131 offset:23040
	ds_read_b128 v[152:155], v131 offset:25600
	ds_read_b128 v[156:159], v131 offset:28160
	ds_read_b128 v[176:179], v238 offset:64
	ds_read_b128 v[180:183], v238 offset:2624
	s_waitcnt lgkmcnt(8)
	v_mfma_f32_16x16x32_bf16 v[126:129], v[144:147], v[160:163], v[126:129]
	s_waitcnt lgkmcnt(7)
	v_mfma_f32_16x16x32_bf16 v[122:125], v[144:147], v[164:167], v[122:125]
	s_waitcnt lgkmcnt(6)
	v_mfma_f32_16x16x32_bf16 v[118:121], v[144:147], v[168:171], v[118:121]
	s_waitcnt lgkmcnt(5)
	v_mfma_f32_16x16x32_bf16 v[114:117], v[144:147], v[172:175], v[114:117]
	ds_read_b128 v[144:147], v131 offset:20544
	s_waitcnt lgkmcnt(5)
	v_mfma_f32_16x16x32_bf16 v[110:113], v[148:151], v[160:163], v[110:113]
	v_mfma_f32_16x16x32_bf16 v[58:61], v[148:151], v[164:167], v[58:61]
	v_mfma_f32_16x16x32_bf16 v[38:41], v[148:151], v[168:171], v[38:41]
	v_mfma_f32_16x16x32_bf16 v[34:37], v[148:151], v[172:175], v[34:37]
	ds_read_b128 v[148:151], v131 offset:23104
	s_waitcnt lgkmcnt(5)
	v_mfma_f32_16x16x32_bf16 v[30:33], v[152:155], v[160:163], v[30:33]
	v_mfma_f32_16x16x32_bf16 v[26:29], v[152:155], v[164:167], v[26:29]
	v_mfma_f32_16x16x32_bf16 v[22:25], v[152:155], v[168:171], v[22:25]
	v_mfma_f32_16x16x32_bf16 v[18:21], v[152:155], v[172:175], v[18:21]
	ds_read_b128 v[152:155], v131 offset:25664
	s_waitcnt lgkmcnt(5)
	v_mfma_f32_16x16x32_bf16 v[6:9], v[156:159], v[168:171], v[6:9]
	v_mfma_f32_16x16x32_bf16 v[2:5], v[156:159], v[172:175], v[2:5]
	ds_read_b128 v[168:171], v238 offset:5184
	ds_read_b128 v[172:175], v238 offset:7744
	v_mfma_f32_16x16x32_bf16 v[14:17], v[156:159], v[160:163], v[14:17]
	v_mfma_f32_16x16x32_bf16 v[10:13], v[156:159], v[164:167], v[10:13]
	ds_read_b128 v[156:159], v131 offset:28224
	s_waitcnt lgkmcnt(5)
	v_mfma_f32_16x16x32_bf16 v[126:129], v[144:147], v[176:179], v[126:129]
	s_waitcnt lgkmcnt(4)
	v_mfma_f32_16x16x32_bf16 v[110:113], v[148:151], v[176:179], v[110:113]
	s_waitcnt lgkmcnt(3)
	v_mfma_f32_16x16x32_bf16 v[30:33], v[152:155], v[176:179], v[30:33]
	v_mfma_f32_16x16x32_bf16 v[122:125], v[144:147], v[180:183], v[122:125]
	v_mfma_f32_16x16x32_bf16 v[58:61], v[148:151], v[180:183], v[58:61]
	v_mfma_f32_16x16x32_bf16 v[26:29], v[152:155], v[180:183], v[26:29]
	s_waitcnt lgkmcnt(2)
	v_mfma_f32_16x16x32_bf16 v[118:121], v[144:147], v[168:171], v[118:121]
	v_mfma_f32_16x16x32_bf16 v[38:41], v[148:151], v[168:171], v[38:41]
	v_mfma_f32_16x16x32_bf16 v[22:25], v[152:155], v[168:171], v[22:25]
	s_waitcnt lgkmcnt(1)
	v_mfma_f32_16x16x32_bf16 v[114:117], v[144:147], v[172:175], v[114:117]
	v_mfma_f32_16x16x32_bf16 v[34:37], v[148:151], v[172:175], v[34:37]
	v_mfma_f32_16x16x32_bf16 v[18:21], v[152:155], v[172:175], v[18:21]
	s_waitcnt lgkmcnt(0)
	v_mfma_f32_16x16x32_bf16 v[14:17], v[156:159], v[176:179], v[14:17]
	v_mfma_f32_16x16x32_bf16 v[10:13], v[156:159], v[180:183], v[10:13]
	v_mfma_f32_16x16x32_bf16 v[6:9], v[156:159], v[168:171], v[6:9]
	v_mfma_f32_16x16x32_bf16 v[2:5], v[156:159], v[172:175], v[2:5]
	s_cbranch_vccnz .LBB0_675
.LBB0_671:
	s_add_i32 s15, s15, 2
	s_cmp_gt_u32 s15, 13
	s_cselect_b64 s[8:9], -1, 0
	s_and_b64 vcc, exec, s[8:9]
	v_lshl_add_u64 v[138:139], v[134:135], 0, v[0:1]
	v_lshl_add_u64 v[136:137], v[132:133], 0, v[0:1]
	s_waitcnt lgkmcnt(0)
	s_barrier
	s_waitcnt vmcnt(8)
	ds_write_b128 v130, v[42:45]
	ds_write_b128 v130, v[50:53] offset:20480
	ds_write_b128 v130, v[62:65] offset:5120
	ds_write_b128 v130, v[70:73] offset:25600
	ds_write_b128 v130, v[78:81] offset:10240
	ds_write_b128 v130, v[86:89] offset:30720
	ds_write_b128 v130, v[94:97] offset:15360
	ds_write_b128 v130, v[102:105] offset:35840
	s_waitcnt lgkmcnt(0)
	s_cbranch_vccnz .Lgw_skip_4
	v_add_co_u32_e32 v42, vcc, 0x19700000, v138
	s_nop 1
	v_addc_co_u32_e32 v43, vcc, 0, v139, vcc
	v_add_co_u32_e32 v50, vcc, 0xa6e0000, v136
	global_load_dwordx4 v[42:45], v[42:43], off offset:256
	s_nop 0
	v_addc_co_u32_e32 v51, vcc, 0, v137, vcc
	v_add_co_u32_e32 v62, vcc, 0x19711000, v138
	global_load_dwordx4 v[50:53], v[50:51], off offset:256
	s_nop 0
	v_addc_co_u32_e32 v63, vcc, 0, v139, vcc
	v_add_co_u32_e32 v70, vcc, 0xa6f1000, v136
	global_load_dwordx4 v[62:65], v[62:63], off offset:256
	s_nop 0
	v_addc_co_u32_e32 v71, vcc, 0, v137, vcc
	v_add_co_u32_e32 v78, vcc, 0x19722000, v138
	global_load_dwordx4 v[70:73], v[70:71], off offset:256
	s_nop 0
	v_addc_co_u32_e32 v79, vcc, 0, v139, vcc
	v_add_co_u32_e32 v86, vcc, 0xa702000, v136
	global_load_dwordx4 v[78:81], v[78:79], off offset:256
	s_nop 0
	v_addc_co_u32_e32 v87, vcc, 0, v137, vcc
	v_add_co_u32_e32 v94, vcc, 0x19733000, v138
	global_load_dwordx4 v[86:89], v[86:87], off offset:256
	s_nop 0
	v_addc_co_u32_e32 v95, vcc, 0, v139, vcc
	v_add_co_u32_e32 v102, vcc, 0xa713000, v136
	global_load_dwordx4 v[94:97], v[94:95], off offset:256
	s_nop 0
	v_addc_co_u32_e32 v103, vcc, 0, v137, vcc
	global_load_dwordx4 v[102:105], v[102:103], off offset:256
; DEV f32x4 mfma16(bf16x8 a, bf16x8 b, f32x4 c) { return __builtin_amdgcn_mfma_f32_16x16x32_bf16(a, b, c, 0, 0, 0); }
; #define G_LOAD(RA, RB, KT) { _Pragma("unroll") for (int i = 0; i < 4; i++) { \
;       RA[i] = *(const u32x4*)(Ap + (size_t)(i * 32) * lda + (KT) * 64); RB[i] = *(const u32x4*)(Bp + (size_t)(i * 32) * ldb + (KT) * 64); } }
; #define G_STORE(RA, RB) { _Pragma("unroll") for (int i = 0; i < 4; i++) { \
;       *(u32x4*)(As + (lrow + i * 32) * GLD + lcc * 8) = RA[i]; *(u32x4*)(Bs + (lrow + i * 32) * GLD + lcc * 8) = RB[i]; } }
; template <int TI, int TJ, int KS>
; DEV void mfma_lds(const bf16_t* Arows, int lda, const bf16_t* Brows, int ldb, int i0, int j0, f32x4 (&acc)[TI][TJ]) {
;     ...
;   for (int ks = 0; ks < KS; ks++) {
;     bf16x8 af[TI], bfr[TJ];
; #pragma unroll
;     for (int i = 0; i < TI; i++) af[i] = *(const bf16x8*)(Arows + (i0 + i * 16 + l15) * lda + ks * 32 + quad * 8);
; #pragma unroll
;     for (int j = 0; j < TJ; j++) bfr[j] = *(const bf16x8*)(Brows + (j0 + j * 16 + l15) * ldb + ks * 32 + quad * 8);
; #pragma unroll
;     for (int i = 0; i < TI; i++)
; #pragma unroll
;       for (int j = 0; j < TJ; j++) acc[i][j] = mfma16(af[i], bfr[j], acc[i][j]);
;   }
; template <class Epi>
; DEV void gemm_tile(const bf16_t* __restrict__ A, int lda, const bf16_t* __restrict__ Bt, int ldb, int K, int m0, int n0,
;                    Epi& epi, char* smem) {
;     ...
;   for (int kt = 0; kt < nk; kt += 2) {
;     __syncthreads();
;     G_STORE(ra0, rb0);
;     __syncthreads();
;     if (kt + 2 < nk) G_LOAD(ra0, rb0, kt + 2);
;     mfma_lds<4, 4, 2>(Bs, GLD, As, GLD, wn * 64, wm * 64, acc);
;     __syncthreads();
;     G_STORE(ra1, rb1);
;     __syncthreads();
;     if (kt + 3 < nk) G_LOAD(ra1, rb1, kt + 3);
;     mfma_lds<4, 4, 2>(Bs, GLD, As, GLD, wn * 64, wm * 64, acc);
;   }
.LBB0_673:
	s_barrier
	v_mov_b32_e32 v131, v195
	s_cmp_gt_u32 s15, 12
	v_and_b32_e32 v143, 15, v131
	v_or_b32_e32 v144, v143, v140
	v_and_b32_e32 v148, 48, v131
	v_mul_u32_u24_e32 v131, 0x50, v144
	v_lshl_add_u32 v131, v131, 1, v148
	v_or_b32_e32 v143, v143, v142
	v_mad_u32_u24 v238, v143, s36, v148
	ds_read_b128 v[144:147], v131 offset:20480
	ds_read_b128 v[160:163], v238
	ds_read_b128 v[164:167], v238 offset:2560
	ds_read_b128 v[168:171], v238 offset:5120
	ds_read_b128 v[172:175], v238 offset:7680
	ds_read_b128 v[148:151], v131 offset:23040
	ds_read_b128 v[152:155], v131 offset:25600
	ds_read_b128 v[156:159], v131 offset:28160
	ds_read_b128 v[176:179], v238 offset:64
	ds_read_b128 v[180:183], v238 offset:2624
	s_waitcnt lgkmcnt(8)
	v_mfma_f32_16x16x32_bf16 v[126:129], v[144:147], v[160:163], v[126:129]
	s_waitcnt lgkmcnt(7)
	v_mfma_f32_16x16x32_bf16 v[122:125], v[144:147], v[164:167], v[122:125]
	s_waitcnt lgkmcnt(6)
	v_mfma_f32_16x16x32_bf16 v[118:121], v[144:147], v[168:171], v[118:121]
	s_waitcnt lgkmcnt(5)
	v_mfma_f32_16x16x32_bf16 v[114:117], v[144:147], v[172:175], v[114:117]
	ds_read_b128 v[144:147], v131 offset:20544
	s_waitcnt lgkmcnt(5)
	v_mfma_f32_16x16x32_bf16 v[110:113], v[148:151], v[160:163], v[110:113]
	v_mfma_f32_16x16x32_bf16 v[58:61], v[148:151], v[164:167], v[58:61]
	v_mfma_f32_16x16x32_bf16 v[38:41], v[148:151], v[168:171], v[38:41]
	v_mfma_f32_16x16x32_bf16 v[34:37], v[148:151], v[172:175], v[34:37]
	ds_read_b128 v[148:151], v131 offset:23104
	s_waitcnt lgkmcnt(5)
	v_mfma_f32_16x16x32_bf16 v[30:33], v[152:155], v[160:163], v[30:33]
	v_mfma_f32_16x16x32_bf16 v[26:29], v[152:155], v[164:167], v[26:29]
	v_mfma_f32_16x16x32_bf16 v[22:25], v[152:155], v[168:171], v[22:25]
	v_mfma_f32_16x16x32_bf16 v[18:21], v[152:155], v[172:175], v[18:21]
	ds_read_b128 v[152:155], v131 offset:25664
	s_waitcnt lgkmcnt(5)
	v_mfma_f32_16x16x32_bf16 v[6:9], v[156:159], v[168:171], v[6:9]
	v_mfma_f32_16x16x32_bf16 v[2:5], v[156:159], v[172:175], v[2:5]
	ds_read_b128 v[168:171], v238 offset:5184
	ds_read_b128 v[172:175], v238 offset:7744
	v_mfma_f32_16x16x32_bf16 v[14:17], v[156:159], v[160:163], v[14:17]
	v_mfma_f32_16x16x32_bf16 v[10:13], v[156:159], v[164:167], v[10:13]
	ds_read_b128 v[156:159], v131 offset:28224
	s_waitcnt lgkmcnt(5)
	v_mfma_f32_16x16x32_bf16 v[126:129], v[144:147], v[176:179], v[126:129]
	s_waitcnt lgkmcnt(4)
	v_mfma_f32_16x16x32_bf16 v[110:113], v[148:151], v[176:179], v[110:113]
	s_waitcnt lgkmcnt(3)
	v_mfma_f32_16x16x32_bf16 v[30:33], v[152:155], v[176:179], v[30:33]
	v_mfma_f32_16x16x32_bf16 v[122:125], v[144:147], v[180:183], v[122:125]
	v_mfma_f32_16x16x32_bf16 v[58:61], v[148:151], v[180:183], v[58:61]
	v_mfma_f32_16x16x32_bf16 v[26:29], v[152:155], v[180:183], v[26:29]
	s_waitcnt lgkmcnt(2)
	v_mfma_f32_16x16x32_bf16 v[118:121], v[144:147], v[168:171], v[118:121]
	v_mfma_f32_16x16x32_bf16 v[38:41], v[148:151], v[168:171], v[38:41]
	v_mfma_f32_16x16x32_bf16 v[22:25], v[152:155], v[168:171], v[22:25]
	s_waitcnt lgkmcnt(1)
	v_mfma_f32_16x16x32_bf16 v[114:117], v[144:147], v[172:175], v[114:117]
	v_mfma_f32_16x16x32_bf16 v[34:37], v[148:151], v[172:175], v[34:37]
	v_mfma_f32_16x16x32_bf16 v[18:21], v[152:155], v[172:175], v[18:21]
	s_waitcnt lgkmcnt(0)
	v_mfma_f32_16x16x32_bf16 v[14:17], v[156:159], v[176:179], v[14:17]
	s_barrier
	v_mfma_f32_16x16x32_bf16 v[10:13], v[156:159], v[180:183], v[10:13]
	s_waitcnt vmcnt(8)
	ds_write_b128 v130, v[46:49]
	ds_write_b128 v130, v[54:57] offset:20480
	ds_write_b128 v130, v[66:69] offset:5120
	ds_write_b128 v130, v[74:77] offset:25600
	ds_write_b128 v130, v[82:85] offset:10240
	ds_write_b128 v130, v[90:93] offset:30720
	ds_write_b128 v130, v[98:101] offset:15360
	ds_write_b128 v130, v[106:109] offset:35840
	v_mfma_f32_16x16x32_bf16 v[6:9], v[156:159], v[168:171], v[6:9]
	s_waitcnt lgkmcnt(0)
	v_mfma_f32_16x16x32_bf16 v[2:5], v[156:159], v[172:175], v[2:5]
	s_cbranch_scc1 .LBB0_670
	v_add_co_u32_e32 v46, vcc, 0x19700000, v138
	s_nop 1
	v_addc_co_u32_e32 v47, vcc, 0, v139, vcc
	v_add_co_u32_e32 v54, vcc, 0xa6e0000, v136
	global_load_dwordx4 v[46:49], v[46:47], off offset:384
	s_nop 0
	v_addc_co_u32_e32 v55, vcc, 0, v137, vcc
	v_add_co_u32_e32 v66, vcc, 0x19711000, v138
	global_load_dwordx4 v[54:57], v[54:55], off offset:384
	s_nop 0
	v_addc_co_u32_e32 v67, vcc, 0, v139, vcc
	v_add_co_u32_e32 v74, vcc, 0xa6f1000, v136
	global_load_dwordx4 v[66:69], v[66:67], off offset:384
	s_nop 0
	v_addc_co_u32_e32 v75, vcc, 0, v137, vcc
	v_add_co_u32_e32 v82, vcc, 0x19722000, v138
	global_load_dwordx4 v[74:77], v[74:75], off offset:384
	s_nop 0
	v_addc_co_u32_e32 v83, vcc, 0, v139, vcc
	v_add_co_u32_e32 v90, vcc, 0xa702000, v136
	global_load_dwordx4 v[82:85], v[82:83], off offset:384
	s_nop 0
	v_addc_co_u32_e32 v91, vcc, 0, v137, vcc
	v_add_co_u32_e32 v98, vcc, 0x19733000, v138
	global_load_dwordx4 v[90:93], v[90:91], off offset:384
	s_nop 0
	v_addc_co_u32_e32 v99, vcc, 0, v139, vcc
	v_add_co_u32_e32 v106, vcc, 0xa713000, v136
	global_load_dwordx4 v[98:101], v[98:99], off offset:384
	s_nop 0
	v_addc_co_u32_e32 v107, vcc, 0, v137, vcc
	global_load_dwordx4 v[106:109], v[106:107], off offset:384
	s_branch .LBB0_670

; DEV f32x4 mfma16(bf16x8 a, bf16x8 b, f32x4 c) { return __builtin_amdgcn_mfma_f32_16x16x32_bf16(a, b, c, 0, 0, 0); }
; #define G_LOAD(RA, RB, KT) { _Pragma("unroll") for (int i = 0; i < 4; i++) { \
;       RA[i] = *(const u32x4*)(Ap + (size_t)(i * 32) * lda + (KT) * 64); RB[i] = *(const u32x4*)(Bp + (size_t)(i * 32) * ldb + (KT) * 64); } }
; #define G_STORE(RA, RB) { _Pragma("unroll") for (int i = 0; i < 4; i++) { \
;       *(u32x4*)(As + (lrow + i * 32) * GLD + lcc * 8) = RA[i]; *(u32x4*)(Bs + (lrow + i * 32) * GLD + lcc * 8) = RB[i]; } }
; template <int TI, int TJ, int KS>
; DEV void mfma_lds(const bf16_t* Arows, int lda, const bf16_t* Brows, int ldb, int i0, int j0, f32x4 (&acc)[TI][TJ]) {
;     ...
;   for (int ks = 0; ks < KS; ks++) {
;     bf16x8 af[TI], bfr[TJ];
; #pragma unroll
;     for (int i = 0; i < TI; i++) af[i] = *(const bf16x8*)(Arows + (i0 + i * 16 + l15) * lda + ks * 32 + quad * 8);
; #pragma unroll
;     for (int j = 0; j < TJ; j++) bfr[j] = *(const bf16x8*)(Brows + (j0 + j * 16 + l15) * ldb + ks * 32 + quad * 8);
; #pragma unroll
;     for (int i = 0; i < TI; i++)
; #pragma unroll
;       for (int j = 0; j < TJ; j++) acc[i][j] = mfma16(af[i], bfr[j], acc[i][j]);
;   }
; template <class Epi>
; DEV void gemm_tile(const bf16_t* __restrict__ A, int lda, const bf16_t* __restrict__ Bt, int ldb, int K, int m0, int n0,
;                    Epi& epi, char* smem) {
;     ...
;   for (int kt = 0; kt < nk; kt += 2) {
;     __syncthreads();
;     G_STORE(ra0, rb0);
;     __syncthreads();
;     if (kt + 2 < nk) G_LOAD(ra0, rb0, kt + 2);
;     mfma_lds<4, 4, 2>(Bs, GLD, As, GLD, wn * 64, wm * 64, acc);
;     __syncthreads();
;     G_STORE(ra1, rb1);
;     __syncthreads();
;     if (kt + 3 < nk) G_LOAD(ra1, rb1, kt + 3);
;     mfma_lds<4, 4, 2>(Bs, GLD, As, GLD, wn * 64, wm * 64, acc);
;   }
.LBB0_1038:
	s_barrier
	v_mov_b32_e32 v131, v195
	v_and_b32_e32 v143, 15, v131
	v_or_b32_e32 v144, v143, v141
	v_and_b32_e32 v148, 48, v131
	v_mul_u32_u24_e32 v131, 0x50, v144
	v_lshl_add_u32 v131, v131, 1, v148
	v_or_b32_e32 v143, v143, v142
	v_mad_u32_u24 v238, v143, s36, v148
	v_lshl_add_u64 v[132:133], v[132:133], 0, s[34:35]
	v_lshl_add_u64 v[134:135], v[134:135], 0, s[34:35]
	s_and_b64 vcc, exec, s[8:9]
	ds_read_b128 v[148:151], v131 offset:20480
	ds_read_b128 v[164:167], v238
	ds_read_b128 v[168:171], v238 offset:2560
	ds_read_b128 v[172:175], v238 offset:5120
	ds_read_b128 v[176:179], v238 offset:7680
	ds_read_b128 v[152:155], v131 offset:23040
	ds_read_b128 v[156:159], v131 offset:25600
	ds_read_b128 v[160:163], v131 offset:28160
	ds_read_b128 v[180:183], v238 offset:64
	ds_read_b128 v[184:187], v238 offset:2624
	s_waitcnt lgkmcnt(8)
	v_mfma_f32_16x16x32_bf16 v[114:117], v[148:151], v[164:167], v[114:117]
	s_waitcnt lgkmcnt(7)
	v_mfma_f32_16x16x32_bf16 v[126:129], v[148:151], v[168:171], v[126:129]
	s_waitcnt lgkmcnt(6)
	v_mfma_f32_16x16x32_bf16 v[122:125], v[148:151], v[172:175], v[122:125]
	s_waitcnt lgkmcnt(5)
	v_mfma_f32_16x16x32_bf16 v[118:121], v[148:151], v[176:179], v[118:121]
	ds_read_b128 v[148:151], v131 offset:20544
	s_waitcnt lgkmcnt(5)
	v_mfma_f32_16x16x32_bf16 v[110:113], v[152:155], v[164:167], v[110:113]
	v_mfma_f32_16x16x32_bf16 v[106:109], v[152:155], v[168:171], v[106:109]
	v_mfma_f32_16x16x32_bf16 v[102:105], v[152:155], v[172:175], v[102:105]
	v_mfma_f32_16x16x32_bf16 v[98:101], v[152:155], v[176:179], v[98:101]
	ds_read_b128 v[152:155], v131 offset:23104
	s_waitcnt lgkmcnt(5)
	v_mfma_f32_16x16x32_bf16 v[94:97], v[156:159], v[164:167], v[94:97]
	v_mfma_f32_16x16x32_bf16 v[82:85], v[156:159], v[168:171], v[82:85]
	v_mfma_f32_16x16x32_bf16 v[78:81], v[156:159], v[172:175], v[78:81]
	v_mfma_f32_16x16x32_bf16 v[70:73], v[156:159], v[176:179], v[70:73]
	ds_read_b128 v[156:159], v131 offset:25664
	s_waitcnt lgkmcnt(5)
	v_mfma_f32_16x16x32_bf16 v[66:69], v[160:163], v[172:175], v[66:69]
	v_mfma_f32_16x16x32_bf16 v[90:93], v[160:163], v[176:179], v[90:93]
	ds_read_b128 v[172:175], v238 offset:5184
	ds_read_b128 v[176:179], v238 offset:7744
	v_mfma_f32_16x16x32_bf16 v[86:89], v[160:163], v[164:167], v[86:89]
	v_mfma_f32_16x16x32_bf16 v[74:77], v[160:163], v[168:171], v[74:77]
	ds_read_b128 v[160:163], v131 offset:28224
	s_waitcnt lgkmcnt(5)
	v_mfma_f32_16x16x32_bf16 v[114:117], v[148:151], v[180:183], v[114:117]
	s_waitcnt lgkmcnt(4)
	v_mfma_f32_16x16x32_bf16 v[110:113], v[152:155], v[180:183], v[110:113]
	s_waitcnt lgkmcnt(3)
	v_mfma_f32_16x16x32_bf16 v[94:97], v[156:159], v[180:183], v[94:97]
	v_mfma_f32_16x16x32_bf16 v[126:129], v[148:151], v[184:187], v[126:129]
	v_mfma_f32_16x16x32_bf16 v[106:109], v[152:155], v[184:187], v[106:109]
	v_mfma_f32_16x16x32_bf16 v[82:85], v[156:159], v[184:187], v[82:85]
	s_waitcnt lgkmcnt(2)
	v_mfma_f32_16x16x32_bf16 v[122:125], v[148:151], v[172:175], v[122:125]
	v_mfma_f32_16x16x32_bf16 v[102:105], v[152:155], v[172:175], v[102:105]
	v_mfma_f32_16x16x32_bf16 v[78:81], v[156:159], v[172:175], v[78:81]
	s_waitcnt lgkmcnt(1)
	v_mfma_f32_16x16x32_bf16 v[118:121], v[148:151], v[176:179], v[118:121]
	v_mfma_f32_16x16x32_bf16 v[98:101], v[152:155], v[176:179], v[98:101]
	v_mfma_f32_16x16x32_bf16 v[70:73], v[156:159], v[176:179], v[70:73]
	s_waitcnt lgkmcnt(0)
	v_mfma_f32_16x16x32_bf16 v[86:89], v[160:163], v[180:183], v[86:89]
	v_mfma_f32_16x16x32_bf16 v[74:77], v[160:163], v[184:187], v[74:77]
	v_mfma_f32_16x16x32_bf16 v[66:69], v[160:163], v[172:175], v[66:69]
	v_mfma_f32_16x16x32_bf16 v[90:93], v[160:163], v[176:179], v[90:93]
	s_cbranch_vccnz .LBB0_1043
.LBB0_1039:
	s_add_i32 s14, s14, 2
	s_cmp_gt_u32 s14, 13
	s_cselect_b64 s[8:9], -1, 0
	s_and_b64 vcc, exec, s[8:9]
	v_lshl_add_u64 v[138:139], v[134:135], 0, v[0:1]
	v_lshl_add_u64 v[136:137], v[132:133], 0, v[0:1]
	s_waitcnt lgkmcnt(0)
	s_barrier
	s_waitcnt vmcnt(8)
	ds_write_b128 v130, v[2:5]
	ds_write_b128 v130, v[10:13] offset:20480
	ds_write_b128 v130, v[18:21] offset:5120
	ds_write_b128 v130, v[26:29] offset:25600
	ds_write_b128 v130, v[34:37] offset:10240
	ds_write_b128 v130, v[42:45] offset:30720
	ds_write_b128 v130, v[50:53] offset:15360
	ds_write_b128 v130, v[58:61] offset:35840
	s_waitcnt lgkmcnt(0)
	s_cbranch_vccnz .Lgw_skip_5
	v_add_co_u32_e32 v2, vcc, 0x4200000, v138
	s_nop 1
	v_addc_co_u32_e32 v3, vcc, 0, v139, vcc
	v_add_co_u32_e32 v10, vcc, 0xa300000, v136
	global_load_dwordx4 v[2:5], v[2:3], off offset:256
	s_nop 0
	v_addc_co_u32_e32 v11, vcc, 0, v137, vcc
	v_add_co_u32_e32 v18, vcc, 0x4211000, v138
	global_load_dwordx4 v[10:13], v[10:11], off offset:256
	s_nop 0
	v_addc_co_u32_e32 v19, vcc, 0, v139, vcc
	v_add_co_u32_e32 v26, vcc, 0xa311000, v136
	global_load_dwordx4 v[18:21], v[18:19], off offset:256
	s_nop 0
	v_addc_co_u32_e32 v27, vcc, 0, v137, vcc
	v_add_co_u32_e32 v34, vcc, 0x4222000, v138
	global_load_dwordx4 v[26:29], v[26:27], off offset:256
	s_nop 0
	v_addc_co_u32_e32 v35, vcc, 0, v139, vcc
	v_add_co_u32_e32 v42, vcc, 0xa322000, v136
	global_load_dwordx4 v[34:37], v[34:35], off offset:256
	s_nop 0
	v_addc_co_u32_e32 v43, vcc, 0, v137, vcc
	v_add_co_u32_e32 v50, vcc, 0x4233000, v138
	global_load_dwordx4 v[42:45], v[42:43], off offset:256
	s_nop 0
	v_addc_co_u32_e32 v51, vcc, 0, v139, vcc
	v_add_co_u32_e32 v58, vcc, 0xa333000, v136
	global_load_dwordx4 v[50:53], v[50:51], off offset:256
	s_nop 0
	v_addc_co_u32_e32 v59, vcc, 0, v137, vcc
	global_load_dwordx4 v[58:61], v[58:59], off offset:256
; DEV f32x4 mfma16(bf16x8 a, bf16x8 b, f32x4 c) { return __builtin_amdgcn_mfma_f32_16x16x32_bf16(a, b, c, 0, 0, 0); }
; #define G_LOAD(RA, RB, KT) { _Pragma("unroll") for (int i = 0; i < 4; i++) { \
;       RA[i] = *(const u32x4*)(Ap + (size_t)(i * 32) * lda + (KT) * 64); RB[i] = *(const u32x4*)(Bp + (size_t)(i * 32) * ldb + (KT) * 64); } }
; #define G_STORE(RA, RB) { _Pragma("unroll") for (int i = 0; i < 4; i++) { \
;       *(u32x4*)(As + (lrow + i * 32) * GLD + lcc * 8) = RA[i]; *(u32x4*)(Bs + (lrow + i * 32) * GLD + lcc * 8) = RB[i]; } }
; template <int TI, int TJ, int KS>
; DEV void mfma_lds(const bf16_t* Arows, int lda, const bf16_t* Brows, int ldb, int i0, int j0, f32x4 (&acc)[TI][TJ]) {
;     ...
;   for (int ks = 0; ks < KS; ks++) {
;     bf16x8 af[TI], bfr[TJ];
; #pragma unroll
;     for (int i = 0; i < TI; i++) af[i] = *(const bf16x8*)(Arows + (i0 + i * 16 + l15) * lda + ks * 32 + quad * 8);
; #pragma unroll
;     for (int j = 0; j < TJ; j++) bfr[j] = *(const bf16x8*)(Brows + (j0 + j * 16 + l15) * ldb + ks * 32 + quad * 8);
; #pragma unroll
;     for (int i = 0; i < TI; i++)
; #pragma unroll
;       for (int j = 0; j < TJ; j++) acc[i][j] = mfma16(af[i], bfr[j], acc[i][j]);
;   }
; template <class Epi>
; DEV void gemm_tile(const bf16_t* __restrict__ A, int lda, const bf16_t* __restrict__ Bt, int ldb, int K, int m0, int n0,
;                    Epi& epi, char* smem) {
;     ...
;   for (int kt = 0; kt < nk; kt += 2) {
;     __syncthreads();
;     G_STORE(ra0, rb0);
;     __syncthreads();
;     if (kt + 2 < nk) G_LOAD(ra0, rb0, kt + 2);
;     mfma_lds<4, 4, 2>(Bs, GLD, As, GLD, wn * 64, wm * 64, acc);
;     __syncthreads();
;     G_STORE(ra1, rb1);
;     __syncthreads();
;     if (kt + 3 < nk) G_LOAD(ra1, rb1, kt + 3);
;     mfma_lds<4, 4, 2>(Bs, GLD, As, GLD, wn * 64, wm * 64, acc);
;   }
.LBB0_1041:
	s_barrier
	v_mov_b32_e32 v131, v195
	s_cmp_gt_u32 s14, 12
	v_and_b32_e32 v143, 15, v131
	v_or_b32_e32 v144, v143, v141
	v_and_b32_e32 v148, 48, v131
	v_mul_u32_u24_e32 v131, 0x50, v144
	v_lshl_add_u32 v131, v131, 1, v148
	v_or_b32_e32 v143, v143, v142
	v_mad_u32_u24 v238, v143, s36, v148
	ds_read_b128 v[148:151], v131 offset:20480
	ds_read_b128 v[164:167], v238
	ds_read_b128 v[168:171], v238 offset:2560
	ds_read_b128 v[172:175], v238 offset:5120
	ds_read_b128 v[176:179], v238 offset:7680
	ds_read_b128 v[152:155], v131 offset:23040
	ds_read_b128 v[156:159], v131 offset:25600
	ds_read_b128 v[160:163], v131 offset:28160
	ds_read_b128 v[180:183], v238 offset:64
	ds_read_b128 v[184:187], v238 offset:2624
	s_waitcnt lgkmcnt(8)
	v_mfma_f32_16x16x32_bf16 v[114:117], v[148:151], v[164:167], v[114:117]
	s_waitcnt lgkmcnt(7)
	v_mfma_f32_16x16x32_bf16 v[126:129], v[148:151], v[168:171], v[126:129]
	s_waitcnt lgkmcnt(6)
	v_mfma_f32_16x16x32_bf16 v[122:125], v[148:151], v[172:175], v[122:125]
	s_waitcnt lgkmcnt(5)
	v_mfma_f32_16x16x32_bf16 v[118:121], v[148:151], v[176:179], v[118:121]
	ds_read_b128 v[148:151], v131 offset:20544
	s_waitcnt lgkmcnt(5)
	v_mfma_f32_16x16x32_bf16 v[110:113], v[152:155], v[164:167], v[110:113]
	v_mfma_f32_16x16x32_bf16 v[106:109], v[152:155], v[168:171], v[106:109]
	v_mfma_f32_16x16x32_bf16 v[102:105], v[152:155], v[172:175], v[102:105]
	v_mfma_f32_16x16x32_bf16 v[98:101], v[152:155], v[176:179], v[98:101]
	ds_read_b128 v[152:155], v131 offset:23104
	s_waitcnt lgkmcnt(5)
	v_mfma_f32_16x16x32_bf16 v[94:97], v[156:159], v[164:167], v[94:97]
	v_mfma_f32_16x16x32_bf16 v[82:85], v[156:159], v[168:171], v[82:85]
	v_mfma_f32_16x16x32_bf16 v[78:81], v[156:159], v[172:175], v[78:81]
	v_mfma_f32_16x16x32_bf16 v[70:73], v[156:159], v[176:179], v[70:73]
	ds_read_b128 v[156:159], v131 offset:25664
	s_waitcnt lgkmcnt(5)
	v_mfma_f32_16x16x32_bf16 v[66:69], v[160:163], v[172:175], v[66:69]
	v_mfma_f32_16x16x32_bf16 v[90:93], v[160:163], v[176:179], v[90:93]
	ds_read_b128 v[172:175], v238 offset:5184
	ds_read_b128 v[176:179], v238 offset:7744
	v_mfma_f32_16x16x32_bf16 v[86:89], v[160:163], v[164:167], v[86:89]
	v_mfma_f32_16x16x32_bf16 v[74:77], v[160:163], v[168:171], v[74:77]
	ds_read_b128 v[160:163], v131 offset:28224
	s_waitcnt lgkmcnt(5)
	v_mfma_f32_16x16x32_bf16 v[114:117], v[148:151], v[180:183], v[114:117]
	s_waitcnt lgkmcnt(4)
	v_mfma_f32_16x16x32_bf16 v[110:113], v[152:155], v[180:183], v[110:113]
	s_waitcnt lgkmcnt(3)
	v_mfma_f32_16x16x32_bf16 v[94:97], v[156:159], v[180:183], v[94:97]
	v_mfma_f32_16x16x32_bf16 v[126:129], v[148:151], v[184:187], v[126:129]
	v_mfma_f32_16x16x32_bf16 v[106:109], v[152:155], v[184:187], v[106:109]
	v_mfma_f32_16x16x32_bf16 v[82:85], v[156:159], v[184:187], v[82:85]
	s_waitcnt lgkmcnt(2)
	v_mfma_f32_16x16x32_bf16 v[122:125], v[148:151], v[172:175], v[122:125]
	v_mfma_f32_16x16x32_bf16 v[102:105], v[152:155], v[172:175], v[102:105]
	v_mfma_f32_16x16x32_bf16 v[78:81], v[156:159], v[172:175], v[78:81]
	s_waitcnt lgkmcnt(1)
	v_mfma_f32_16x16x32_bf16 v[118:121], v[148:151], v[176:179], v[118:121]
	v_mfma_f32_16x16x32_bf16 v[98:101], v[152:155], v[176:179], v[98:101]
	v_mfma_f32_16x16x32_bf16 v[70:73], v[156:159], v[176:179], v[70:73]
	s_waitcnt lgkmcnt(0)
	v_mfma_f32_16x16x32_bf16 v[86:89], v[160:163], v[180:183], v[86:89]
	s_barrier
	v_mfma_f32_16x16x32_bf16 v[74:77], v[160:163], v[184:187], v[74:77]
	s_waitcnt vmcnt(8)
	ds_write_b128 v130, v[6:9]
	ds_write_b128 v130, v[14:17] offset:20480
	ds_write_b128 v130, v[22:25] offset:5120
	ds_write_b128 v130, v[30:33] offset:25600
	ds_write_b128 v130, v[38:41] offset:10240
	ds_write_b128 v130, v[46:49] offset:30720
	ds_write_b128 v130, v[54:57] offset:15360
	ds_write_b128 v130, v[62:65] offset:35840
	v_mfma_f32_16x16x32_bf16 v[66:69], v[160:163], v[172:175], v[66:69]
	s_waitcnt lgkmcnt(0)
	v_mfma_f32_16x16x32_bf16 v[90:93], v[160:163], v[176:179], v[90:93]
	s_cbranch_scc1 .LBB0_1038
	v_add_co_u32_e32 v6, vcc, 0x4200000, v138
	s_nop 1
	v_addc_co_u32_e32 v7, vcc, 0, v139, vcc
	v_add_co_u32_e32 v14, vcc, 0xa300000, v136
	global_load_dwordx4 v[6:9], v[6:7], off offset:384
	s_nop 0
	v_addc_co_u32_e32 v15, vcc, 0, v137, vcc
	v_add_co_u32_e32 v22, vcc, 0x4211000, v138
	global_load_dwordx4 v[14:17], v[14:15], off offset:384
	s_nop 0
	v_addc_co_u32_e32 v23, vcc, 0, v139, vcc
	v_add_co_u32_e32 v30, vcc, 0xa311000, v136
	global_load_dwordx4 v[22:25], v[22:23], off offset:384
	s_nop 0
	v_addc_co_u32_e32 v31, vcc, 0, v137, vcc
	v_add_co_u32_e32 v38, vcc, 0x4222000, v138
	global_load_dwordx4 v[30:33], v[30:31], off offset:384
	s_nop 0
	v_addc_co_u32_e32 v39, vcc, 0, v139, vcc
	v_add_co_u32_e32 v46, vcc, 0xa322000, v136
	global_load_dwordx4 v[38:41], v[38:39], off offset:384
	s_nop 0
	v_addc_co_u32_e32 v47, vcc, 0, v137, vcc
	v_add_co_u32_e32 v54, vcc, 0x4233000, v138
	global_load_dwordx4 v[46:49], v[46:47], off offset:384
	s_nop 0
	v_addc_co_u32_e32 v55, vcc, 0, v139, vcc
	v_add_co_u32_e32 v62, vcc, 0xa333000, v136
	global_load_dwordx4 v[54:57], v[54:55], off offset:384
	s_nop 0
	v_addc_co_u32_e32 v63, vcc, 0, v137, vcc
	global_load_dwordx4 v[62:65], v[62:63], off offset:384
	s_branch .LBB0_1038
